# attn-C: softmax tail (row max, rescale test, p0 scale-fma) moved into PV MFMA gaps, p0 exp deferred into next QK segment, K/V LDS staging writes moved to first PV gaps
# speedup vs baseline: 1.0089x; 1.0068x over previous
; __device__ __forceinline__ int tid_() { int t = (int)threadIdx.x; asm volatile("" : "+v"(t)); return t; }
; __device__ __forceinline__ int v_st(int k, int c) { const int kk = (k & ~0xC) | ((k & 4) << 1) | ((k & 8) >> 1); return ((kk >> 3) * 4 + (c >> 5)) * 512 + ((kk & 7) * 32 + (c & 31)) * 2; }
; __device__ __forceinline__ int v_rd_base(int lane) { return ((lane & 3) << 3) | (((lane >> 2) & 3) << 6) | (((lane >> 4) & 1) << 5) | (((lane >> 5) & 1) << 8); }
; __device__ __forceinline__ void qkt(f32x16& p0, f32x16& p1, const bf16_t* Ks, const bf16x8* qr, int r32, int hi) {
;     p0 = f32x16{}; p1 = f32x16{};
; #pragma unroll
;     for (int d0 = 0; d0 < 8; ++d0) { int cb = (d0 * 16 + hi * 8) * 2;
;         bf16x8 b0 = *reinterpret_cast<const bf16x8*>((const char*)Ks + KSWZ(r32, cb));
;         bf16x8 b1 = *reinterpret_cast<const bf16x8*>((const char*)Ks + KSWZ(32 + r32, cb));
;         p0 = __builtin_amdgcn_mfma_f32_32x32x16_bf16(b0, qr[d0], p0, 0, 0, 0);
;         p1 = __builtin_amdgcn_mfma_f32_32x32x16_bf16(b1, qr[d0], p1, 0, 0, 0); }
; __device__ __forceinline__ void attn_dense_body(const bf16_t* __restrict__ Qb, const bf16_t* __restrict__ Kh, const bf16_t* __restrict__ Vh,
;                                                 bf16_t* __restrict__ Ob, int seq, char* lds, int dry) {
;     const int tid = tid_(), wid = tid >> 6, lane = tid & 63, r32 = lane & 31, hi = lane >> 5;
;     bf16_t* V_lds = (bf16_t*)lds; bf16_t* K_lds = (bf16_t*)(lds + 3 * SHM_V);
;     float* ws = (float*)(lds + 3 * SHM_V + 3 * SHM_K) + wid * 64; float* li_l = ws; float* al_l = ws + 32;
;     float m_reg = -1e30f, l_reg = 0; f32x16 o[4] = {}; bf16x8 qr[8];
;     const bf16_t* Qw = Qb + (long)(wid * QBLK + r32) * LDQ + hi * 8;
; #pragma unroll
;     for (int d0 = 0; d0 < 8; ++d0) qr[d0] = *reinterpret_cast<const bf16x8*>(Qw + d0 * 16);
;     const int sr = tid >> 4, sc = (tid & 15) * 8, vst0 = v_st(sr, sc), vst1 = v_st(32 + sr, sc);
;     const int vb0 = (int)(uintptr_t)V_lds + v_rd_base(lane);
;     bf16x8 sv0[2], sv1[2], sk0[2], sk1[2];
;     ...
;     f32x16 pA0, pA1, pB0, pB1; float mnA, mnB, alA, alB; bf16x8 pa0, pa1, pa2, pa3; const int NT = seq / KVBLK;
;     SLOAD(0, 0); asm volatile("s_waitcnt vmcnt(0)" ::: "memory"); SWRITE(0, 0); __syncthreads();
;     qkt(pA0, pA1, K_lds, qr, r32, hi); partialSM(pA0, pA1, m_reg, mnA, alA);
.LBB0_268:
	s_lshl_b32 s4, s29, 5
	s_cmpk_lt_i32 s29, 0x400
	s_movk_i32 s7, 0xc000
	s_cselect_b32 s5, 6, 4
	s_cselect_b32 s6, 63, 15
	s_cselect_b32 s7, s7, 0x7ffff000
	s_movk_i32 s37, 0x4000
	s_cselect_b32 s8, s37, 0xffff8000
	s_cselect_b32 s36, 0x100, 64
	s_lshr_b32 s12, s29, s5
	s_and_b32 s5, s6, s29
	s_and_b32 s4, s7, s4
	s_add_i32 s8, s4, s8
	s_lshl_b32 s4, s5, 8
	s_add_i32 s4, s8, s4
	s_and_b32 s6, s12, 7
	s_ashr_i32 s5, s4, 31
	s_mul_i32 s9, s4, 0xc00
	s_mul_hi_i32 s7, s4, 0xc00
	s_add_u32 s9, s30, s9
	s_addc_u32 s7, s31, s7
	s_lshl_b32 s35, s6, 7
	s_lshl_b32 s6, s6, 8
	s_add_u32 s10, s9, s6
	s_addc_u32 s11, s7, 0
	s_ashr_i32 s9, s8, 31
	s_mul_i32 s7, s8, 0xc00
	s_mul_hi_i32 s6, s8, 0xc00
	s_add_u32 s7, s30, s7
	s_addc_u32 s13, s31, s6
	s_lshl_b32 s6, s12, 6
	s_and_b32 s39, s6, 0x100
	v_mov_b32_e32 v70, v182
	s_add_u32 s6, s7, s39
	s_addc_u32 s7, s13, 0
	v_ashrrev_i32_e32 v48, 4, v70
	v_lshlrev_b32_e32 v18, 3, v70
	v_and_b32_e32 v71, 0x78, v18
	s_waitcnt vmcnt(0)
	v_mad_i64_i32 v[0:1], s[12:13], v48, s71, 0
	v_add_u32_e32 v19, 32, v48
	v_or_b32_e32 v0, v0, v71
	v_lshl_add_u64 v[8:9], v[0:1], 1, s[6:7]
	v_mad_i64_i32 v[4:5], s[12:13], v19, s71, 0
	global_load_dwordx4 v[0:3], v[8:9], off offset:2560
	v_or_b32_e32 v4, v4, v71
	v_lshl_add_u64 v[12:13], v[4:5], 1, s[6:7]
	global_load_dwordx4 v[4:7], v[12:13], off offset:2560
	s_nop 0
	global_load_dwordx4 v[8:11], v[8:9], off offset:2048
	s_nop 0
	global_load_dwordx4 v[12:15], v[12:13], off offset:2048
	v_ashrrev_i32_e32 v49, 1, v70
	s_movk_i32 s12, 0xffe0
	v_bfe_u32 v207, v70, 5, 1
	v_bfi_b32 v20, s12, v49, v70
	v_mov_b64_e32 v[16:17], s[10:11]
	v_mad_i64_i32 v[16:17], s[10:11], v20, s70, v[16:17]
	v_lshlrev_b32_e32 v96, 4, v207
	v_lshl_add_u64 v[16:17], v[16:17], 0, v[96:97]
	global_load_dwordx4 v[126:129], v[16:17], off
	global_load_dwordx4 v[122:125], v[16:17], off offset:32
	global_load_dwordx4 v[118:121], v[16:17], off offset:64
	global_load_dwordx4 v[114:117], v[16:17], off offset:96
	global_load_dwordx4 v[110:113], v[16:17], off offset:128
	global_load_dwordx4 v[106:109], v[16:17], off offset:160
	global_load_dwordx4 v[102:105], v[16:17], off offset:192
	global_load_dwordx4 v[98:101], v[16:17], off offset:224
	v_and_b32_e32 v21, 0xfffff0, v48
	v_lshlrev_b32_e32 v22, 1, v48
	v_lshrrev_b32_e32 v23, 1, v48
	v_and_b32_e32 v24, 3, v48
	v_and_or_b32 v21, v22, 8, v21
	v_and_or_b32 v22, v23, 4, v24
	v_and_b32_e32 v24, 0xfffff0, v19
	v_lshlrev_b32_e32 v26, 1, v19
	v_bfe_u32 v18, v18, 5, 2
	v_lshrrev_b32_e32 v21, 1, v21
	v_and_or_b32 v24, v26, 8, v24
	v_lshlrev_b32_e32 v23, 1, v71
	v_or_b32_e32 v21, v21, v18
	v_lshrrev_b32_e32 v24, 1, v24
	v_lshlrev_b32_e32 v22, 6, v22
	v_and_b32_e32 v27, 48, v23
	v_lshlrev_b32_e32 v21, 9, v21
	v_or_b32_e32 v18, v24, v18
	v_and_b32_e32 v20, 0x70, v70
	v_lshlrev_b32_e32 v25, 8, v48
	v_or3_b32 v216, v21, v22, v27
	v_lshlrev_b32_e32 v18, 9, v18
	v_bitop3_b32 v214, v23, v25, v20 bitop3:0xde
	v_and_b32_e32 v252, 0x80, v182
	v_lshlrev_b32_e32 v253, 4, v182
	v_and_b32_e32 v253, 0x80, v253
	v_xor_b32_e32 v214, v214, v252
	v_or3_b32 v217, v18, v22, v27
	v_add_u32_e32 v72, 0, v216
	v_and_b32_e32 v208, 31, v70
	v_lshlrev_b32_e32 v50, 4, v70
	v_add_u32_e32 v73, 0, v217
	s_waitcnt vmcnt(0)
	s_add_i32 s10, 0, 0x18000
	v_and_b32_e32 v74, 63, v70
	s_cmp_lg_u32 0, -1
	s_mov_b32 s12, 0
	s_mov_b32 s13, s12
	v_and_b32_e32 v178, 0xffffffe0, v49
	s_waitcnt vmcnt(11)
	ds_write_b128 v72, v[0:3]
	s_waitcnt vmcnt(10)
	ds_write_b128 v73, v[4:7]
	v_add_u32_e32 v0, 0, v214
	s_waitcnt vmcnt(9)
	ds_write_b128 v0, v[8:11] offset:49152
	v_lshlrev_b32_e32 v0, 8, v19
	v_lshlrev_b32_e32 v8, 8, v208
	v_and_b32_e32 v9, 0x70, v50
	v_bitop3_b32 v219, v23, v0, v20 bitop3:0xde
	v_xor_b32_e32 v219, v219, v252
	v_bitop3_b32 v220, v96, v8, v9 bitop3:0xde
	v_xor_b32_e32 v220, v220, v253
	v_add_u32_e32 v0, 0, v219
	v_add_u32_e32 v4, 0, v220
	s_waitcnt vmcnt(8)
	ds_write_b128 v0, v[12:15] offset:49152
	s_waitcnt lgkmcnt(0)
	s_barrier
	ds_read_b128 v[0:3], v4 offset:49152
	ds_read_b128 v[4:7], v4 offset:57344
	s_waitcnt vmcnt(7) lgkmcnt(1)
	v_mfma_f32_32x32x16_bf16 v[16:31], v[0:3], v[126:129], 0
	v_or_b32_e32 v0, 32, v96
	v_bitop3_b32 v222, v0, v8, v9 bitop3:0xde
	v_xor_b32_e32 v222, v222, v253
	v_ashrrev_i32_e32 v49, 31, v48
	s_mov_b32 s14, s12
	s_mov_b32 s15, s12
	s_mov_b32 s16, s12
	s_mov_b32 s17, s12
	s_waitcnt lgkmcnt(0)
	v_mfma_f32_32x32x16_bf16 v[32:47], v[4:7], v[126:129], 0
	v_add_u32_e32 v4, 0, v222
	ds_read_b128 v[0:3], v4 offset:49152
	ds_read_b128 v[4:7], v4 offset:57344
	s_mov_b32 s18, s12
	s_mov_b32 s19, s12
	s_mov_b32 s20, s12
	s_mov_b32 s21, s12
	s_mov_b32 s22, s12
	s_waitcnt vmcnt(6) lgkmcnt(1)
	v_mfma_f32_32x32x16_bf16 v[16:31], v[0:3], v[122:125], v[16:31]
	v_or_b32_e32 v0, 64, v96
	v_bitop3_b32 v221, v0, v8, v9 bitop3:0xde
	v_xor_b32_e32 v221, v221, v253
	s_mov_b32 s23, s12
	s_mov_b32 s24, s12
	s_mov_b32 s25, s12
	s_mov_b32 s26, s12
	s_mov_b32 s27, s12
	s_waitcnt lgkmcnt(0)
	v_mfma_f32_32x32x16_bf16 v[32:47], v[4:7], v[122:125], v[32:47]
	v_add_u32_e32 v4, 0, v221
	ds_read_b128 v[0:3], v4 offset:49152
	ds_read_b128 v[4:7], v4 offset:57344
	s_mov_b32 s38, 2
	v_mov_b32_e32 v210, 0
	s_waitcnt vmcnt(5) lgkmcnt(1)
	v_mfma_f32_32x32x16_bf16 v[16:31], v[0:3], v[118:121], v[16:31]
	v_or_b32_e32 v0, 0x60, v96
	v_bitop3_b32 v218, v0, v8, v9 bitop3:0xde
	v_xor_b32_e32 v218, v218, v253
	s_waitcnt lgkmcnt(0)
	v_mfma_f32_32x32x16_bf16 v[32:47], v[4:7], v[118:121], v[32:47]
	v_add_u32_e32 v4, 0, v218
	ds_read_b128 v[0:3], v4 offset:49152
	ds_read_b128 v[4:7], v4 offset:57344
	s_waitcnt vmcnt(4) lgkmcnt(1)
; #define SLOAD(i, k0) do { sv0[i] = *(const bf16x8*)(&Vh[(long)((k0) + sr) * LDK + sc]); sv1[i] = *(const bf16x8*)(&Vh[(long)((k0) + 32 + sr) * LDK + sc]); \
;     sk0[i] = *(const bf16x8*)(&Kh[(long)((k0) + sr) * LDK + sc]); sk1[i] = *(const bf16x8*)(&Kh[(long)((k0) + 32 + sr) * LDK + sc]); } while (0)
; #define SWRITE(off, i) do { *(bf16x8*)((char*)V_lds + (off) + vst0) = sv0[i];          \
;     *(bf16x8*)((char*)V_lds + (off) + vst1) = sv1[i]; int kc = sc * 2;               \
;     *(bf16x8*)((char*)K_lds + (off) + KSWZ(sr, kc)) = sk0[i];                       \
;     *(bf16x8*)((char*)K_lds + (off) + KSWZ(32 + sr, kc)) = sk1[i]; } while (0)
; #define SWAIT() asm volatile("s_waitcnt vmcnt(4)" ::: "memory")
; __device__ __forceinline__ void partialSM(f32x16& p0, f32x16& p1, float& m_reg, float& mn, float& alpha) {
;     constexpr float C = SCALE * 1.4426950408889634f;
;     float pmax = p0[0];
; #pragma unroll
;     for (int r = 1; r < 16; ++r) pmax = fmaxf(pmax, p0[r]);
; #pragma unroll
;     for (int r = 0; r < 16; ++r) pmax = fmaxf(pmax, p1[r]);
;     { auto rr = __builtin_amdgcn_permlane32_swap(__float_as_uint(pmax), __float_as_uint(pmax), false, false);
;       pmax = fmaxf(__uint_as_float(rr[0]), __uint_as_float(rr[1])); }
;     if (__builtin_expect(__all(pmax - m_reg <= THR / SCALE), 1)) { mn = m_reg; alpha = 1.f; }
;     else { mn = fmaxf(m_reg, pmax); alpha = __builtin_amdgcn_exp2f((m_reg - mn) * C); m_reg = mn; }
; __device__ __forceinline__ void attn_dense_body(const bf16_t* __restrict__ Qb, const bf16_t* __restrict__ Kh, const bf16_t* __restrict__ Vh,
;                                                 bf16_t* __restrict__ Ob, int seq, char* lds, int dry) {
;     ...
;     qkt(pA0, pA1, K_lds, qr, r32, hi); partialSM(pA0, pA1, m_reg, mnA, alA);
;     SLOAD(1, KVBLK); if (2 < NT) SLOAD(0, 2 * KVBLK);
;     SWAIT(); SWRITE((int)SHM_K, 1); __syncthreads();
	v_mfma_f32_32x32x16_bf16 v[16:31], v[0:3], v[114:117], v[16:31]
	v_or_b32_e32 v0, 0x80, v96
	v_bitop3_b32 v215, v0, v8, v9 bitop3:0xde
	v_xor_b32_e32 v215, v215, v253
	s_waitcnt lgkmcnt(0)
	v_mfma_f32_32x32x16_bf16 v[32:47], v[4:7], v[114:117], v[32:47]
	v_add_u32_e32 v4, 0, v215
	ds_read_b128 v[0:3], v4 offset:49152
	ds_read_b128 v[4:7], v4 offset:57344
	s_waitcnt vmcnt(3) lgkmcnt(1)
	v_mfma_f32_32x32x16_bf16 v[16:31], v[0:3], v[110:113], v[16:31]
	v_or_b32_e32 v0, 0xa0, v96
	v_bitop3_b32 v213, v0, v8, v9 bitop3:0xde
	v_xor_b32_e32 v213, v213, v253
	s_waitcnt lgkmcnt(0)
	v_mfma_f32_32x32x16_bf16 v[32:47], v[4:7], v[110:113], v[32:47]
	v_add_u32_e32 v4, 0, v213
	ds_read_b128 v[0:3], v4 offset:49152
	v_and_b32_e32 v5, 0x3fffffc0, v70
	v_lshl_add_u32 v179, v5, 2, s10
	ds_read_b128 v[4:7], v4 offset:57344
	v_lshl_add_u32 v209, v208, 2, v179
	s_waitcnt vmcnt(2) lgkmcnt(1)
	v_mfma_f32_32x32x16_bf16 v[16:31], v[0:3], v[106:109], v[16:31]
	v_lshlrev_b32_e32 v0, 3, v74
	v_and_b32_e32 v1, 0xc0, v50
	v_and_or_b32 v10, v0, 24, v1
	v_lshlrev_b32_e32 v1, 1, v70
	v_and_b32_e32 v12, 0x100, v0
	v_add_u32_e32 v0, 64, v48
	v_and_b32_e32 v11, 32, v1
	s_waitcnt lgkmcnt(0)
	v_mfma_f32_32x32x16_bf16 v[32:47], v[4:7], v[106:109], v[32:47]
	v_or_b32_e32 v6, 0xc0, v96
	v_mad_i64_i32 v[0:1], s[10:11], v0, s71, 0
	v_add_u32_e32 v2, 0x60, v48
	v_or_b32_e32 v0, v0, v71
	v_mad_i64_i32 v[2:3], s[10:11], v2, s71, 0
	v_bitop3_b32 v223, v6, v8, v9 bitop3:0xde
	v_xor_b32_e32 v223, v223, v253
	v_lshl_add_u64 v[0:1], v[0:1], 1, s[6:7]
	v_or_b32_e32 v2, v2, v71
	v_add_u32_e32 v6, 0, v223
	global_load_dwordx4 v[50:53], v[0:1], off offset:2560
	global_load_dwordx4 v[58:61], v[0:1], off offset:2048
	v_lshl_add_u64 v[4:5], v[2:3], 1, s[6:7]
	ds_read_b128 v[0:3], v6 offset:49152
	s_waitcnt vmcnt(3) lgkmcnt(0)
	v_mfma_f32_32x32x16_bf16 v[16:31], v[0:3], v[102:105], v[16:31]
	v_or_b32_e32 v0, 0xe0, v96
	v_bitop3_b32 v224, v0, v8, v9 bitop3:0xde
	v_xor_b32_e32 v224, v224, v253
	global_load_dwordx4 v[54:57], v[4:5], off offset:2560
	global_load_dwordx4 v[62:65], v[4:5], off offset:2048
	v_or3_b32 v4, v10, v11, v12
	s_cselect_b32 s10, 0, 0
	v_add_u32_e32 v8, 0, v224
	v_add_u32_e32 v212, s10, v4
	ds_read_b128 v[4:7], v6 offset:57344
	ds_read_b128 v[0:3], v8 offset:49152
	ds_read_b128 v[66:69], v8 offset:57344
	s_waitcnt lgkmcnt(2)
	v_mfma_f32_32x32x16_bf16 v[32:47], v[4:7], v[102:105], v[32:47]
	s_waitcnt vmcnt(4) lgkmcnt(1)
	v_mfma_f32_32x32x16_bf16 v[16:31], v[0:3], v[98:101], v[16:31]
	v_mov_b64_e32 v[0:1], s[12:13]
	v_mov_b64_e32 v[2:3], s[14:15]
	v_mov_b64_e32 v[4:5], s[16:17]
	v_mov_b64_e32 v[6:7], s[18:19]
	v_mov_b64_e32 v[8:9], s[20:21]
	v_mov_b64_e32 v[10:11], s[22:23]
	v_mov_b64_e32 v[12:13], s[24:25]
	s_waitcnt lgkmcnt(0)
	v_mfma_f32_32x32x16_bf16 v[32:47], v[66:69], v[98:101], v[32:47]
	s_nop 2
	v_max_f32_e32 v66, v17, v17
	v_max_f32_e32 v67, v16, v16
	v_max_f32_e32 v66, v67, v66
	v_max3_f32 v66, v66, v18, v19
	v_max3_f32 v66, v66, v20, v21
	v_max3_f32 v66, v66, v22, v23
	v_max3_f32 v66, v66, v24, v25
	v_max3_f32 v66, v66, v26, v27
	v_max3_f32 v66, v66, v28, v29
	v_max3_f32 v66, v66, v30, v31
	v_max3_f32 v66, v66, v32, v33
	v_max3_f32 v66, v66, v34, v35
	v_max3_f32 v66, v66, v36, v37
	v_max3_f32 v66, v66, v38, v39
	v_max3_f32 v66, v66, v40, v41
	v_max3_f32 v66, v66, v42, v43
	v_max3_f32 v66, v66, v44, v45
	v_max3_f32 v75, v66, v46, v47
	v_mov_b32_e32 v66, v75
	s_nop 1
	v_permlane32_swap_b32_e32 v75, v66
	v_max_f32_e32 v76, v66, v66
	v_add_u32_e32 v66, 0xa0, v48
	v_mad_i64_i32 v[66:67], s[10:11], v66, s71, 0
	v_add_u32_e32 v68, 0x80, v48
	v_or_b32_e32 v66, v66, v71
	v_mad_i64_i32 v[68:69], s[10:11], v68, s71, 0
	v_lshl_add_u64 v[66:67], v[66:67], 1, s[6:7]
	v_or_b32_e32 v68, v68, v71
	v_lshl_add_u64 v[68:69], v[68:69], 1, s[6:7]
	global_load_dwordx4 v[130:133], v[66:67], off offset:2048
	global_load_dwordx4 v[142:145], v[66:67], off offset:2560
	global_load_dwordx4 v[138:141], v[68:69], off offset:2048
	global_load_dwordx4 v[134:137], v[68:69], off offset:2560
	v_max_f32_e32 v66, v75, v75
	v_max_f32_e32 v66, v66, v76
	v_add_f32_e32 v67, 0x7149f2ca, v66
	s_add_i32 s6, 0, 0x10000
	v_cmp_ge_f32_e32 vcc, s72, v67
	s_waitcnt vmcnt(4)
	s_waitcnt vmcnt(7)
	ds_write_b128 v72, v[50:53] offset:16384
	s_waitcnt vmcnt(5)
	ds_write_b128 v73, v[54:57] offset:16384
	v_add_u32_e32 v50, s6, v214
	ds_write_b128 v50, v[58:61]
	v_add_u32_e32 v50, s6, v219
	s_cmp_eq_u64 vcc, exec
	s_waitcnt vmcnt(4)
; __device__ __forceinline__ void partialSM(f32x16& p0, f32x16& p1, float& m_reg, float& mn, float& alpha) {
;     ...
;     else { mn = fmaxf(m_reg, pmax); alpha = __builtin_amdgcn_exp2f((m_reg - mn) * C); m_reg = mn; }
;     float mnC = -mn * C;
; #pragma unroll
;     for (int r = 0; r < 16; ++r) p0[r] = fmaf(p0[r], C, mnC);
; #pragma unroll
;     for (int r = 0; r < 16; ++r) p1[r] = fmaf(p1[r], C, mnC);
; #pragma unroll
;     for (int r = 0; r < 16; ++r) p0[r] = __builtin_amdgcn_exp2f(p0[r]);
; }
; __device__ __forceinline__ void finishSM(f32x16& p0, f32x16& p1, float alpha, float& l_reg, bf16x8& pa0, bf16x8& pa1, bf16x8& pa2, bf16x8& pa3) {
; #pragma unroll
;     for (int r = 0; r < 16; ++r) p1[r] = __builtin_amdgcn_exp2f(p1[r]);
;     float ps = 0;
; #pragma unroll
;     for (int r = 0; r < 16; ++r) ps += p0[r];
; #pragma unroll
;     for (int r = 0; r < 16; ++r) ps += p1[r];
;     { auto rr = __builtin_amdgcn_permlane32_swap(__float_as_uint(ps), __float_as_uint(ps), false, false);
;       ps = __uint_as_float(rr[0]) + __uint_as_float(rr[1]); }
;     l_reg = l_reg * alpha + ps;
;     ...
;     PK4(p0, 0, pa0); PK4(p0, 8, pa1); PK4(p1, 0, pa2); PK4(p1, 8, pa3);
;     ...
; }
; __device__ __forceinline__ void qkt(f32x16& p0, f32x16& p1, const bf16_t* Ks, const bf16x8* qr, int r32, int hi) {
;     p0 = f32x16{}; p1 = f32x16{};
; #pragma unroll
;     for (int d0 = 0; d0 < 8; ++d0) { int cb = (d0 * 16 + hi * 8) * 2;
;         bf16x8 b0 = *reinterpret_cast<const bf16x8*>((const char*)Ks + KSWZ(r32, cb));
;         bf16x8 b1 = *reinterpret_cast<const bf16x8*>((const char*)Ks + KSWZ(32 + r32, cb));
;         p0 = __builtin_amdgcn_mfma_f32_32x32x16_bf16(b0, qr[d0], p0, 0, 0, 0);
;         p1 = __builtin_amdgcn_mfma_f32_32x32x16_bf16(b1, qr[d0], p1, 0, 0, 0); }
	ds_write_b128 v50, v[62:65]
	v_max_f32_e32 v50, 0xf149f2ca, v66
	s_cselect_b64 vcc, -1, 0
	v_cndmask_b32_e32 v166, v50, v198, vcc
	v_sub_f32_e32 v51, 0xf149f2ca, v50
	v_mul_f32_e32 v50, 0xbe0293ee, v166
	v_fmamk_f32 v16, v16, 0x3e0293ee, v50
	v_mov_b32_e32 v163, v16
	v_fmamk_f32 v16, v17, 0x3e0293ee, v50
	v_mov_b32_e32 v177, v16
	v_fmamk_f32 v16, v18, 0x3e0293ee, v50
	v_mov_b32_e32 v164, v16
	v_fmamk_f32 v16, v19, 0x3e0293ee, v50
	v_mov_b32_e32 v229, v16
	v_fmamk_f32 v16, v20, 0x3e0293ee, v50
	v_mov_b32_e32 v176, v16
	v_fmamk_f32 v16, v21, 0x3e0293ee, v50
	v_mov_b32_e32 v230, v16
	v_fmamk_f32 v16, v22, 0x3e0293ee, v50
	v_mov_b32_e32 v165, v16
	v_fmamk_f32 v16, v23, 0x3e0293ee, v50
	v_mov_b32_e32 v175, v16
	v_fmamk_f32 v16, v24, 0x3e0293ee, v50
	v_mov_b32_e32 v171, v16
	v_fmamk_f32 v16, v25, 0x3e0293ee, v50
	v_mov_b32_e32 v173, v16
	v_fmamk_f32 v16, v26, 0x3e0293ee, v50
	v_mul_f32_e32 v51, 0x3e0293ee, v51
	v_mov_b32_e32 v172, v16
	v_fmamk_f32 v16, v27, 0x3e0293ee, v50
	v_exp_f32_e32 v51, v51
	v_mov_b32_e32 v174, v16
	v_fmamk_f32 v16, v28, 0x3e0293ee, v50
	v_mov_b32_e32 v167, v16
	v_fmamk_f32 v16, v29, 0x3e0293ee, v50
	v_mov_b32_e32 v169, v16
	v_fmamk_f32 v16, v30, 0x3e0293ee, v50
	v_mov_b64_e32 v[14:15], s[26:27]
	s_mov_b32 s20, 0x3e0293ee
	v_mov_b32_e32 v168, v16
	v_lshl_add_u64 v[16:17], v[48:49], 0, s[8:9]
	v_pk_fma_f32 v[146:147], v[46:47], s[20:21], v[50:51] op_sel_hi:[1,0,0]
	v_pk_fma_f32 v[148:149], v[44:45], s[20:21], v[50:51] op_sel_hi:[1,0,0]
	v_pk_fma_f32 v[150:151], v[42:43], s[20:21], v[50:51] op_sel_hi:[1,0,0]
	v_pk_fma_f32 v[152:153], v[40:41], s[20:21], v[50:51] op_sel_hi:[1,0,0]
	v_pk_fma_f32 v[154:155], v[38:39], s[20:21], v[50:51] op_sel_hi:[1,0,0]
	v_pk_fma_f32 v[156:157], v[36:37], s[20:21], v[50:51] op_sel_hi:[1,0,0]
	v_pk_fma_f32 v[158:159], v[34:35], s[20:21], v[50:51] op_sel_hi:[1,0,0]
	v_pk_fma_f32 v[160:161], v[32:33], s[20:21], v[50:51] op_sel_hi:[1,0,0]
	v_fmac_f32_e32 v50, 0x3e0293ee, v31
	v_mad_u64_u32 v[18:19], s[8:9], v16, s70, 0
	v_and_b32_e32 v16, 15, v70
	v_mov_b32_e32 v170, v50
	v_lshlrev_b32_e32 v16, 4, v16
	v_mad_i32_i24 v17, v17, s70, v19
	v_or3_b32 v16, v18, s39, v16
	v_cndmask_b32_e64 v225, v51, 1.0, vcc
	v_lshl_add_u64 v[180:181], s[2:3], 0, v[16:17]
	v_mov_b64_e32 v[62:63], v[14:15]
	v_mov_b64_e32 v[46:47], v[14:15]
	v_mov_b64_e32 v[30:31], v[14:15]
	v_cmp_gt_u32_e64 s[6:7], 32, v74
	s_mov_b32 s8, 0x8000
	v_mov_b64_e32 v[60:61], v[12:13]
	v_mov_b64_e32 v[58:59], v[10:11]
	v_mov_b64_e32 v[56:57], v[8:9]
	v_mov_b64_e32 v[54:55], v[6:7]
	v_mov_b64_e32 v[52:53], v[4:5]
	v_mov_b64_e32 v[50:51], v[2:3]
	v_mov_b64_e32 v[48:49], v[0:1]
	v_mov_b64_e32 v[44:45], v[12:13]
	v_mov_b64_e32 v[42:43], v[10:11]
	v_mov_b64_e32 v[40:41], v[8:9]
	v_mov_b64_e32 v[38:39], v[6:7]
	v_mov_b64_e32 v[36:37], v[4:5]
	v_mov_b64_e32 v[34:35], v[2:3]
	v_mov_b64_e32 v[32:33], v[0:1]
	v_mov_b64_e32 v[28:29], v[12:13]
	v_mov_b64_e32 v[26:27], v[10:11]
	v_mov_b64_e32 v[24:25], v[8:9]
	v_mov_b64_e32 v[22:23], v[6:7]
	v_mov_b64_e32 v[20:21], v[4:5]
	v_mov_b64_e32 v[18:19], v[2:3]
	v_mov_b64_e32 v[16:17], v[0:1]
	s_waitcnt lgkmcnt(0)
	s_barrier
.LBB0_269:
	s_mov_b32 s13, s12
	s_mov_b32 s12, s8
	s_add_i32 s8, s37, 0
	v_add_u32_e32 v71, s8, v220
	ds_read_b128 v[64:67], v71 offset:49152
	ds_read_b128 v[68:71], v71 offset:57344
	v_add_u32_e32 v239, s8, v222
	ds_read_b128 v[232:235], v239 offset:49152
	ds_read_b128 v[236:239], v239 offset:57344
	v_add_u32_e32 v247, s8, v221
	ds_read_b128 v[240:243], v247 offset:49152
	ds_read_b128 v[244:247], v247 offset:57344
	s_waitcnt lgkmcnt(5)
	v_mfma_f32_32x32x16_bf16 v[80:95], v[64:67], v[126:129], 0
	v_exp_f32_e32 v163, v163
	v_exp_f32_e32 v177, v177
	v_exp_f32_e32 v164, v164
	v_exp_f32_e32 v229, v229
	v_exp_f32_e32 v176, v176
	v_exp_f32_e32 v230, v230
	s_waitcnt lgkmcnt(4)
	v_mfma_f32_32x32x16_bf16 v[64:79], v[68:71], v[126:129], 0
	v_exp_f32_e32 v165, v165
	v_exp_f32_e32 v175, v175
	v_exp_f32_e32 v171, v171
	v_exp_f32_e32 v173, v173
	v_exp_f32_e32 v172, v172
	v_exp_f32_e32 v174, v174
	s_waitcnt lgkmcnt(3)
	v_mfma_f32_32x32x16_bf16 v[80:95], v[232:235], v[122:125], v[80:95]
	v_exp_f32_e32 v167, v167
	v_exp_f32_e32 v169, v169
	v_exp_f32_e32 v168, v168
	v_exp_f32_e32 v170, v170
	v_add_f32_e32 v162, 0, v163
	v_exp_f32_e32 v160, v160
	s_waitcnt lgkmcnt(2)
	v_mfma_f32_32x32x16_bf16 v[64:79], v[236:239], v[122:125], v[64:79]
	v_add_u32_e32 v239, s8, v218
	ds_read_b128 v[232:235], v239 offset:49152
	ds_read_b128 v[236:239], v239 offset:57344
	v_add_f32_e32 v162, v177, v162
	v_exp_f32_e32 v161, v161
	v_add_f32_e32 v162, v164, v162
	v_exp_f32_e32 v158, v158
	v_add_f32_e32 v162, v229, v162
	v_exp_f32_e32 v159, v159
	s_waitcnt lgkmcnt(3)
	v_mfma_f32_32x32x16_bf16 v[80:95], v[240:243], v[118:121], v[80:95]
	v_add_f32_e32 v162, v176, v162
	v_exp_f32_e32 v156, v156
	v_add_f32_e32 v162, v230, v162
	v_exp_f32_e32 v157, v157
	v_add_f32_e32 v162, v165, v162
	v_exp_f32_e32 v154, v154
	s_waitcnt lgkmcnt(2)
	v_mfma_f32_32x32x16_bf16 v[64:79], v[244:247], v[118:121], v[64:79]
	v_add_u32_e32 v247, s8, v215
	ds_read_b128 v[240:243], v247 offset:49152
	ds_read_b128 v[244:247], v247 offset:57344
	v_add_f32_e32 v162, v175, v162
	v_exp_f32_e32 v155, v155
	v_add_f32_e32 v162, v171, v162
	v_exp_f32_e32 v152, v152
	v_add_f32_e32 v162, v173, v162
	v_exp_f32_e32 v153, v153
	s_waitcnt lgkmcnt(3)
	v_mfma_f32_32x32x16_bf16 v[80:95], v[232:235], v[114:117], v[80:95]
	v_add_f32_e32 v162, v172, v162
	v_exp_f32_e32 v150, v150
	v_add_f32_e32 v162, v174, v162
	v_exp_f32_e32 v151, v151
	v_add_f32_e32 v162, v167, v162
	v_exp_f32_e32 v148, v148
	s_waitcnt lgkmcnt(2)
; __device__ __forceinline__ void finishSM(f32x16& p0, f32x16& p1, float alpha, float& l_reg, bf16x8& pa0, bf16x8& pa1, bf16x8& pa2, bf16x8& pa3) {
; #pragma unroll
;     for (int r = 0; r < 16; ++r) p1[r] = __builtin_amdgcn_exp2f(p1[r]);
;     float ps = 0;
; #pragma unroll
;     for (int r = 0; r < 16; ++r) ps += p0[r];
; #pragma unroll
;     for (int r = 0; r < 16; ++r) ps += p1[r];
;     { auto rr = __builtin_amdgcn_permlane32_swap(__float_as_uint(ps), __float_as_uint(ps), false, false);
;       ps = __uint_as_float(rr[0]) + __uint_as_float(rr[1]); }
;     l_reg = l_reg * alpha + ps;
;     ...
;     PK4(p0, 0, pa0); PK4(p0, 8, pa1); PK4(p1, 0, pa2); PK4(p1, 8, pa3);
;     ...
; }
; __device__ __forceinline__ void qkt(f32x16& p0, f32x16& p1, const bf16_t* Ks, const bf16x8* qr, int r32, int hi) {
;     p0 = f32x16{}; p1 = f32x16{};
; #pragma unroll
;     for (int d0 = 0; d0 < 8; ++d0) { int cb = (d0 * 16 + hi * 8) * 2;
;         bf16x8 b0 = *reinterpret_cast<const bf16x8*>((const char*)Ks + KSWZ(r32, cb));
;         bf16x8 b1 = *reinterpret_cast<const bf16x8*>((const char*)Ks + KSWZ(32 + r32, cb));
;         p0 = __builtin_amdgcn_mfma_f32_32x32x16_bf16(b0, qr[d0], p0, 0, 0, 0);
;         p1 = __builtin_amdgcn_mfma_f32_32x32x16_bf16(b1, qr[d0], p1, 0, 0, 0); }
; }
; __device__ __forceinline__ int v_st(int k, int c) { const int kk = (k & ~0xC) | ((k & 4) << 1) | ((k & 8) >> 1); return ((kk >> 3) * 4 + (c >> 5)) * 512 + ((kk & 7) * 32 + (c & 31)) * 2; }
; __device__ __forceinline__ int v_rd_base(int lane) { return ((lane & 3) << 3) | (((lane >> 2) & 3) << 6) | (((lane >> 4) & 1) << 5) | (((lane >> 5) & 1) << 8); }
; template <int OFF> __device__ __forceinline__ s16x4 tr_read(int vb) {
;     s16x4 r; asm volatile("ds_read_b64_tr_b16 %0, %1 offset:%2" : "=&v"(r) : "v"(vb), "i"(OFF) : "memory"); return r;
; }
; template <int D0> __device__ __forceinline__ void pv_one(f32x16& od, int vb, bf16x8 pa0, bf16x8 pa1, bf16x8 pa2, bf16x8 pa3) {
;     const s16x4 l0 = tr_read<v_rd_off(D0, 0, 0)>(vb), h0 = tr_read<v_rd_off(D0, 0, 1)>(vb), l1 = tr_read<v_rd_off(D0, 1, 0)>(vb), h1 = tr_read<v_rd_off(D0, 1, 1)>(vb);
;     const s16x4 l2 = tr_read<v_rd_off(D0, 2, 0)>(vb), h2 = tr_read<v_rd_off(D0, 2, 1)>(vb), l3 = tr_read<v_rd_off(D0, 3, 0)>(vb), h3 = tr_read<v_rd_off(D0, 3, 1)>(vb);
;     asm volatile("s_waitcnt lgkmcnt(0)" ::: "memory"); SBAR();
	v_mfma_f32_32x32x16_bf16 v[64:79], v[236:239], v[114:117], v[64:79]
	v_add_u32_e32 v239, s8, v213
	ds_read_b128 v[232:235], v239 offset:49152
	ds_read_b128 v[236:239], v239 offset:57344
	v_add_f32_e32 v162, v169, v162
	v_exp_f32_e32 v149, v149
	v_add_f32_e32 v162, v168, v162
	v_exp_f32_e32 v146, v146
	v_add_f32_e32 v162, v170, v162
	v_exp_f32_e32 v147, v147
	s_waitcnt lgkmcnt(3)
	v_mfma_f32_32x32x16_bf16 v[80:95], v[240:243], v[110:113], v[80:95]
	v_add_f32_e32 v162, v160, v162
	v_add_f32_e32 v162, v161, v162
	v_add_f32_e32 v162, v158, v162
	v_add_f32_e32 v162, v159, v162
	v_add_f32_e32 v162, v156, v162
	v_add_f32_e32 v162, v157, v162
	s_waitcnt lgkmcnt(2)
	v_mfma_f32_32x32x16_bf16 v[64:79], v[244:247], v[110:113], v[64:79]
	v_add_u32_e32 v247, s8, v223
	ds_read_b128 v[240:243], v247 offset:49152
	ds_read_b128 v[244:247], v247 offset:57344
	v_add_f32_e32 v162, v154, v162
	v_add_f32_e32 v162, v155, v162
	v_add_f32_e32 v162, v152, v162
	v_add_f32_e32 v162, v153, v162
	v_add_f32_e32 v162, v150, v162
	v_add_f32_e32 v162, v151, v162
	s_waitcnt lgkmcnt(3)
	v_mfma_f32_32x32x16_bf16 v[80:95], v[232:235], v[106:109], v[80:95]
	v_add_f32_e32 v162, v148, v162
	v_add_f32_e32 v162, v149, v162
	v_add_f32_e32 v162, v146, v162
	v_add_f32_e32 v226, v147, v162
	v_mov_b32_e32 v227, v226
	s_waitcnt lgkmcnt(2)
	v_mfma_f32_32x32x16_bf16 v[64:79], v[236:239], v[106:109], v[64:79]
	v_add_u32_e32 v239, s8, v224
	ds_read_b128 v[232:235], v239 offset:49152
	ds_read_b128 v[236:239], v239 offset:57344
	v_cvt_pk_bf16_f32 v162, v163, v177
	v_cvt_pk_bf16_f32 v163, v164, v229
	v_cvt_pk_bf16_f32 v164, v176, v230
	v_cvt_pk_bf16_f32 v165, v165, v175
	v_cvt_pk_bf16_f32 v228, v171, v173
	s_waitcnt lgkmcnt(3)
	v_mfma_f32_32x32x16_bf16 v[80:95], v[240:243], v[102:105], v[80:95]
	v_cvt_pk_bf16_f32 v229, v172, v174
	v_cvt_pk_bf16_f32 v230, v167, v169
	v_permlane32_swap_b32_e32 v226, v227
	v_permlane32_swap_b32_e32 v162, v164
	v_cvt_pk_bf16_f32 v231, v168, v170
	s_waitcnt lgkmcnt(2)
	v_mfma_f32_32x32x16_bf16 v[64:79], v[244:247], v[102:105], v[64:79]
	v_permlane32_swap_b32_e32 v228, v230
	v_cvt_pk_bf16_f32 v168, v160, v161
	v_cvt_pk_bf16_f32 v169, v158, v159
	v_cvt_pk_bf16_f32 v170, v156, v157
	v_cvt_pk_bf16_f32 v171, v154, v155
	s_waitcnt lgkmcnt(1)
	v_mfma_f32_32x32x16_bf16 v[80:95], v[232:235], v[98:101], v[80:95]
	v_cvt_pk_bf16_f32 v172, v152, v153
	v_cvt_pk_bf16_f32 v173, v150, v151
	v_cvt_pk_bf16_f32 v174, v148, v149
	v_cvt_pk_bf16_f32 v175, v146, v147
	v_permlane32_swap_b32_e32 v163, v165
	s_waitcnt lgkmcnt(0)
	v_mfma_f32_32x32x16_bf16 v[64:79], v[236:239], v[98:101], v[64:79]
	v_permlane32_swap_b32_e32 v229, v231
	v_permlane32_swap_b32_e32 v168, v170
	v_permlane32_swap_b32_e32 v169, v171
	v_permlane32_swap_b32_e32 v172, v174
	v_permlane32_swap_b32_e32 v173, v175
	s_mov_b32 s8, 0xfffb8000
	v_add_co_u32_e32 v150, vcc, s8, v180
	s_mov_b32 s8, 0xfffd0000
	s_nop 0
	v_addc_co_u32_e32 v151, vcc, -1, v181, vcc
	v_add_co_u32_e32 v154, vcc, s8, v180
	s_nop 1
	v_addc_co_u32_e32 v155, vcc, -1, v181, vcc
	global_load_dwordx4 v[146:149], v[150:151], off
	s_nop 0
	global_load_dwordx4 v[150:153], v[150:151], off offset:-512
	s_nop 0
	global_load_dwordx4 v[158:161], v[154:155], off
	s_nop 0
	global_load_dwordx4 v[154:157], v[154:155], off offset:-512
	v_add_u32_e32 v211, s13, v212
	ds_read_b64_tr_b16 v[232:233], v211 offset:0x0
	ds_read_b64_tr_b16 v[234:235], v211 offset:0x800
	ds_read_b64_tr_b16 v[236:237], v211 offset:0x1000
	ds_read_b64_tr_b16 v[238:239], v211 offset:0x1800
	ds_read_b64_tr_b16 v[240:241], v211 offset:0x2000
	ds_read_b64_tr_b16 v[242:243], v211 offset:0x2800
	ds_read_b64_tr_b16 v[244:245], v211 offset:0x3000
	ds_read_b64_tr_b16 v[246:247], v211 offset:0x3800
	s_waitcnt lgkmcnt(0)
	s_nop 0
	v_mfma_f32_32x32x16_bf16 v[0:15], v[162:165], v[232:235], v[0:15]
	ds_read_b64_tr_b16 v[232:233], v211 offset:0x200
	ds_read_b64_tr_b16 v[234:235], v211 offset:0xa00
	s_add_i32 s14, s12, 0
	s_waitcnt vmcnt(4)
	v_add_u32_e32 v253, s14, v216
	ds_write_b128 v253, v[134:137]
	v_mfma_f32_32x32x16_bf16 v[0:15], v[228:231], v[236:239], v[0:15]
	ds_read_b64_tr_b16 v[236:237], v211 offset:0x1200
	ds_read_b64_tr_b16 v[238:239], v211 offset:0x1a00
	v_add_u32_e32 v253, s14, v217
	ds_write_b128 v253, v[142:145]
	v_mfma_f32_32x32x16_bf16 v[0:15], v[168:171], v[240:243], v[0:15]
	ds_read_b64_tr_b16 v[240:241], v211 offset:0x2200
	ds_read_b64_tr_b16 v[242:243], v211 offset:0x2a00
	v_add_u32_e32 v253, s14, v214
	ds_write_b128 v253, v[138:141] offset:49152
	v_mfma_f32_32x32x16_bf16 v[0:15], v[172:175], v[244:247], v[0:15]
	ds_read_b64_tr_b16 v[244:245], v211 offset:0x3200
	ds_read_b64_tr_b16 v[246:247], v211 offset:0x3a00
	v_add_u32_e32 v253, s14, v219
	ds_write_b128 v253, v[130:133] offset:49152
	s_waitcnt lgkmcnt(0)
	v_mfma_f32_32x32x16_bf16 v[48:63], v[162:165], v[232:235], v[48:63]
	ds_read_b64_tr_b16 v[232:233], v211 offset:0x400
	ds_read_b64_tr_b16 v[234:235], v211 offset:0xc00
	v_max_f32_e32 v248, v81, v81
	v_max_f32_e32 v249, v80, v80
	v_max_f32_e32 v248, v249, v248
	v_max3_f32 v248, v248, v82, v83
	v_max3_f32 v248, v248, v84, v85
	v_mfma_f32_32x32x16_bf16 v[48:63], v[228:231], v[236:239], v[48:63]
	ds_read_b64_tr_b16 v[236:237], v211 offset:0x1400
	ds_read_b64_tr_b16 v[238:239], v211 offset:0x1c00
	v_max3_f32 v248, v248, v86, v87
	v_max3_f32 v248, v248, v88, v89
	v_max3_f32 v248, v248, v90, v91
	v_max3_f32 v248, v248, v92, v93
	v_max3_f32 v248, v248, v94, v95
	v_mfma_f32_32x32x16_bf16 v[48:63], v[168:171], v[240:243], v[48:63]
	ds_read_b64_tr_b16 v[240:241], v211 offset:0x2400
	ds_read_b64_tr_b16 v[242:243], v211 offset:0x2c00
	v_max3_f32 v248, v248, v64, v65
	v_max3_f32 v248, v248, v66, v67
	v_max3_f32 v248, v248, v68, v69
	v_max3_f32 v248, v248, v70, v71
	v_max3_f32 v248, v248, v72, v73
	v_mfma_f32_32x32x16_bf16 v[48:63], v[172:175], v[244:247], v[48:63]
	ds_read_b64_tr_b16 v[244:245], v211 offset:0x3400
	ds_read_b64_tr_b16 v[246:247], v211 offset:0x3c00
	v_max3_f32 v248, v248, v74, v75
	v_max3_f32 v248, v248, v76, v77
	v_max3_f32 v248, v248, v78, v79
	v_mov_b32_e32 v249, v248
	s_waitcnt lgkmcnt(0)
; __device__ __forceinline__ void partialSM(f32x16& p0, f32x16& p1, float& m_reg, float& mn, float& alpha) {
;     constexpr float C = SCALE * 1.4426950408889634f;
;     float pmax = p0[0];
; #pragma unroll
;     for (int r = 1; r < 16; ++r) pmax = fmaxf(pmax, p0[r]);
; #pragma unroll
;     for (int r = 0; r < 16; ++r) pmax = fmaxf(pmax, p1[r]);
;     { auto rr = __builtin_amdgcn_permlane32_swap(__float_as_uint(pmax), __float_as_uint(pmax), false, false);
;       pmax = fmaxf(__uint_as_float(rr[0]), __uint_as_float(rr[1])); }
;     if (__builtin_expect(__all(pmax - m_reg <= THR / SCALE), 1)) { mn = m_reg; alpha = 1.f; }
;     else { mn = fmaxf(m_reg, pmax); alpha = __builtin_amdgcn_exp2f((m_reg - mn) * C); m_reg = mn; }
;     float mnC = -mn * C;
; #pragma unroll
;     for (int r = 0; r < 16; ++r) p0[r] = fmaf(p0[r], C, mnC);
; #pragma unroll
;     for (int r = 0; r < 16; ++r) p1[r] = fmaf(p1[r], C, mnC);
; #pragma unroll
;     for (int r = 0; r < 16; ++r) p0[r] = __builtin_amdgcn_exp2f(p0[r]);
	v_mfma_f32_32x32x16_bf16 v[32:47], v[162:165], v[232:235], v[32:47]
	ds_read_b64_tr_b16 v[232:233], v211 offset:0x600
	ds_read_b64_tr_b16 v[234:235], v211 offset:0xe00
	v_permlane32_swap_b32_e32 v248, v249
	v_max_f32_e32 v249, v249, v249
	v_max_f32_e32 v248, v248, v248
	v_max_f32_e32 v248, v248, v249
	v_mfma_f32_32x32x16_bf16 v[32:47], v[228:231], v[236:239], v[32:47]
	ds_read_b64_tr_b16 v[236:237], v211 offset:0x1600
	ds_read_b64_tr_b16 v[238:239], v211 offset:0x1e00
	v_sub_f32_e32 v249, v248, v166
	v_cmp_ge_f32_e32 vcc, s72, v249
	v_max_f32_e32 v249, v166, v166
	v_max_f32_e32 v248, v249, v248
	v_sub_f32_e32 v249, v166, v248
	v_mfma_f32_32x32x16_bf16 v[32:47], v[168:171], v[240:243], v[32:47]
	ds_read_b64_tr_b16 v[240:241], v211 offset:0x2600
	ds_read_b64_tr_b16 v[242:243], v211 offset:0x2e00
	v_mul_f32_e32 v249, 0x3e0293ee, v249
	v_exp_f32_e32 v249, v249
	v_mfma_f32_32x32x16_bf16 v[32:47], v[172:175], v[244:247], v[32:47]
	ds_read_b64_tr_b16 v[244:245], v211 offset:0x3600
	ds_read_b64_tr_b16 v[246:247], v211 offset:0x3e00
	s_cmp_eq_u64 vcc, exec
	s_cselect_b64 s[8:9], -1, 0
	s_nop 0
	v_cndmask_b32_e64 v167, v249, 1.0, s[8:9]
	v_cndmask_b32_e64 v176, v248, v166, s[8:9]
	v_mul_f32_e32 v177, 0xbe0293ee, v176
	s_waitcnt lgkmcnt(0)
	v_mfma_f32_32x32x16_bf16 v[16:31], v[162:165], v[232:235], v[16:31]
	v_fmamk_f32 v250, v92, 0x3e0293ee, v177
	v_fmamk_f32 v251, v93, 0x3e0293ee, v177
	v_fmamk_f32 v252, v94, 0x3e0293ee, v177
	v_fmamk_f32 v253, v95, 0x3e0293ee, v177
	v_mfma_f32_32x32x16_bf16 v[16:31], v[228:231], v[236:239], v[16:31]
	v_fmamk_f32 v248, v90, 0x3e0293ee, v177
	v_fmamk_f32 v249, v91, 0x3e0293ee, v177
	v_fmamk_f32 v238, v80, 0x3e0293ee, v177
	v_fmamk_f32 v239, v81, 0x3e0293ee, v177
	v_mfma_f32_32x32x16_bf16 v[16:31], v[168:171], v[240:243], v[16:31]
	v_fmamk_f32 v240, v82, 0x3e0293ee, v177
	v_fmamk_f32 v241, v83, 0x3e0293ee, v177
	v_fmamk_f32 v242, v84, 0x3e0293ee, v177
	v_fmamk_f32 v243, v85, 0x3e0293ee, v177
	v_mfma_f32_32x32x16_bf16 v[16:31], v[172:175], v[244:247], v[16:31]
	v_fmamk_f32 v244, v86, 0x3e0293ee, v177
	v_fmamk_f32 v245, v87, 0x3e0293ee, v177
	v_fmamk_f32 v246, v88, 0x3e0293ee, v177
	v_fmamk_f32 v247, v89, 0x3e0293ee, v177
	v_mov_b32_e32 v228, v167
	s_nop 0
	v_cmp_gt_f32_e32 vcc, 1.0, v228
	s_cbranch_vccz .LBB0_273
	s_and_saveexec_b64 s[10:11], s[6:7]
	ds_write_b32 v209, v228 offset:128
	s_or_b64 exec, exec, s[10:11]
	s_waitcnt lgkmcnt(0)
	v_add_u32_e32 v163, v179, v96
	ds_read_b128 v[168:171], v163 offset:224
	ds_read_b128 v[172:175], v163 offset:192
	ds_read_b128 v[230:233], v163 offset:160
	ds_read_b128 v[234:237], v163 offset:128
	s_waitcnt lgkmcnt(3)
	v_pk_mul_f32 v[12:13], v[12:13], v[168:169]
	s_waitcnt lgkmcnt(2)
	v_pk_mul_f32 v[8:9], v[8:9], v[172:173]
	s_waitcnt lgkmcnt(1)
	v_pk_mul_f32 v[4:5], v[4:5], v[230:231]
	v_pk_mul_f32 v[14:15], v[14:15], v[170:171]
	v_pk_mul_f32 v[10:11], v[10:11], v[174:175]
	v_pk_mul_f32 v[6:7], v[6:7], v[232:233]
	s_waitcnt lgkmcnt(0)
	v_pk_mul_f32 v[2:3], v[2:3], v[236:237]
	v_pk_mul_f32 v[0:1], v[0:1], v[234:235]
	v_pk_mul_f32 v[60:61], v[60:61], v[168:169]
	v_pk_mul_f32 v[56:57], v[56:57], v[172:173]
	v_pk_mul_f32 v[52:53], v[52:53], v[230:231]
	v_pk_mul_f32 v[62:63], v[62:63], v[170:171]
	v_pk_mul_f32 v[58:59], v[58:59], v[174:175]
	v_pk_mul_f32 v[54:55], v[54:55], v[232:233]
	v_pk_mul_f32 v[50:51], v[50:51], v[236:237]
	v_pk_mul_f32 v[48:49], v[48:49], v[234:235]
	v_pk_mul_f32 v[44:45], v[44:45], v[168:169]
	v_pk_mul_f32 v[40:41], v[40:41], v[172:173]
	v_pk_mul_f32 v[36:37], v[36:37], v[230:231]
	v_pk_mul_f32 v[46:47], v[46:47], v[170:171]
	v_pk_mul_f32 v[42:43], v[42:43], v[174:175]
	v_pk_mul_f32 v[38:39], v[38:39], v[232:233]
	v_pk_mul_f32 v[34:35], v[34:35], v[236:237]
	v_pk_mul_f32 v[32:33], v[32:33], v[234:235]
	v_pk_mul_f32 v[28:29], v[28:29], v[168:169]
	v_pk_mul_f32 v[24:25], v[24:25], v[172:173]
	v_pk_mul_f32 v[20:21], v[20:21], v[230:231]
	v_pk_mul_f32 v[30:31], v[30:31], v[170:171]
	v_pk_mul_f32 v[26:27], v[26:27], v[174:175]
	v_pk_mul_f32 v[22:23], v[22:23], v[232:233]
	v_pk_mul_f32 v[18:19], v[18:19], v[236:237]
	v_pk_mul_f32 v[16:17], v[16:17], v[234:235]
.LBB0_273:
	v_mov_b32_e32 v229, v176
	v_fmamk_f32 v171, v64, 0x3e0293ee, v177
	v_fmamk_f32 v172, v65, 0x3e0293ee, v177
	v_fmamk_f32 v173, v66, 0x3e0293ee, v177
	v_fmamk_f32 v174, v67, 0x3e0293ee, v177
	v_fmamk_f32 v175, v68, 0x3e0293ee, v177
	v_fmamk_f32 v176, v69, 0x3e0293ee, v177
	v_fmamk_f32 v230, v71, 0x3e0293ee, v177
	v_fmamk_f32 v231, v72, 0x3e0293ee, v177
	v_fmamk_f32 v232, v73, 0x3e0293ee, v177
	v_fmamk_f32 v233, v74, 0x3e0293ee, v177
	v_fmamk_f32 v234, v75, 0x3e0293ee, v177
	v_fmamk_f32 v235, v76, 0x3e0293ee, v177
	v_fmamk_f32 v236, v77, 0x3e0293ee, v177
	v_fmamk_f32 v237, v78, 0x3e0293ee, v177
	v_fmamk_f32 v170, v79, 0x3e0293ee, v177
	v_fmac_f32_e32 v177, 0x3e0293ee, v70
	s_waitcnt lgkmcnt(0)
	s_barrier
; #define SBAR() __builtin_amdgcn_sched_barrier(0)
; #define SLOAD(i, k0) do { sv0[i] = *(const bf16x8*)(&Vh[(long)((k0) + sr) * LDK + sc]); sv1[i] = *(const bf16x8*)(&Vh[(long)((k0) + 32 + sr) * LDK + sc]); \
;     sk0[i] = *(const bf16x8*)(&Kh[(long)((k0) + sr) * LDK + sc]); sk1[i] = *(const bf16x8*)(&Kh[(long)((k0) + 32 + sr) * LDK + sc]); } while (0)
; __device__ __forceinline__ void finishSM(f32x16& p0, f32x16& p1, float alpha, float& l_reg, bf16x8& pa0, bf16x8& pa1, bf16x8& pa2, bf16x8& pa3) {
; #pragma unroll
;     for (int r = 0; r < 16; ++r) p1[r] = __builtin_amdgcn_exp2f(p1[r]);
;     float ps = 0;
; #pragma unroll
;     for (int r = 0; r < 16; ++r) ps += p0[r];
; #pragma unroll
;     for (int r = 0; r < 16; ++r) ps += p1[r];
;     { auto rr = __builtin_amdgcn_permlane32_swap(__float_as_uint(ps), __float_as_uint(ps), false, false);
;       ps = __uint_as_float(rr[0]) + __uint_as_float(rr[1]); }
;     l_reg = l_reg * alpha + ps;
;     ...
;     PK4(p0, 0, pa0); PK4(p0, 8, pa1); PK4(p1, 0, pa2); PK4(p1, 8, pa3);
;     ...
; }
; __device__ __forceinline__ void qkt(f32x16& p0, f32x16& p1, const bf16_t* Ks, const bf16x8* qr, int r32, int hi) {
;     p0 = f32x16{}; p1 = f32x16{};
; #pragma unroll
;     for (int d0 = 0; d0 < 8; ++d0) { int cb = (d0 * 16 + hi * 8) * 2;
;         bf16x8 b0 = *reinterpret_cast<const bf16x8*>((const char*)Ks + KSWZ(r32, cb));
;         bf16x8 b1 = *reinterpret_cast<const bf16x8*>((const char*)Ks + KSWZ(32 + r32, cb));
;         p0 = __builtin_amdgcn_mfma_f32_32x32x16_bf16(b0, qr[d0], p0, 0, 0, 0);
;         p1 = __builtin_amdgcn_mfma_f32_32x32x16_bf16(b1, qr[d0], p1, 0, 0, 0); }
; __device__ __forceinline__ void attn_dense_body(const bf16_t* __restrict__ Qb, const bf16_t* __restrict__ Kh, const bf16_t* __restrict__ Vh,
;                                                 bf16_t* __restrict__ Ob, int seq, char* lds, int dry) {
;     ...
;         SBAR(); qkt(pA0, pA1, (bf16_t*)((char*)K_lds + oq), qr, r32, hi);
;         finishSM(pB0, pB1, alB, l_reg, pa0, pa1, pa2, pa3); SBAR();
;         if (j + 3 < NT) SLOAD(0, (j + 3) * KVBLK); SBAR();
;         pv_d0(o, vb0 + ov, pa0, pa1, pa2, pa3); partialSM(pA0, pA1, m_reg, mnA, alA);
	v_add_u32_e32 v71, s14, v220
	ds_read_b128 v[64:67], v71 offset:49152
	ds_read_b128 v[68:71], v71 offset:57344
	v_add_u32_e32 v137, s14, v222
	ds_read_b128 v[130:133], v137 offset:49152
	ds_read_b128 v[134:137], v137 offset:57344
	v_add_u32_e32 v145, s14, v221
	ds_read_b128 v[138:141], v145 offset:49152
	ds_read_b128 v[142:145], v145 offset:57344
	s_waitcnt lgkmcnt(5)
	v_mfma_f32_32x32x16_bf16 v[80:95], v[64:67], v[126:129], 0
	v_exp_f32_e32 v238, v238
	v_exp_f32_e32 v239, v239
	v_exp_f32_e32 v240, v240
	v_exp_f32_e32 v241, v241
	v_exp_f32_e32 v242, v242
	v_exp_f32_e32 v243, v243
	s_waitcnt lgkmcnt(4)
	v_mfma_f32_32x32x16_bf16 v[64:79], v[68:71], v[126:129], 0
	v_exp_f32_e32 v244, v244
	v_exp_f32_e32 v245, v245
	v_exp_f32_e32 v246, v246
	v_exp_f32_e32 v247, v247
	v_exp_f32_e32 v248, v248
	v_exp_f32_e32 v249, v249
	s_waitcnt lgkmcnt(3)
	v_mfma_f32_32x32x16_bf16 v[80:95], v[130:133], v[122:125], v[80:95]
	v_exp_f32_e32 v250, v250
	v_exp_f32_e32 v251, v251
	v_exp_f32_e32 v252, v252
	v_exp_f32_e32 v253, v253
	v_add_f32_e32 v162, 0, v238
	v_exp_f32_e32 v171, v171
	s_waitcnt lgkmcnt(2)
	v_mfma_f32_32x32x16_bf16 v[64:79], v[134:137], v[122:125], v[64:79]
	v_add_u32_e32 v137, s14, v218
	ds_read_b128 v[130:133], v137 offset:49152
	ds_read_b128 v[134:137], v137 offset:57344
	v_add_f32_e32 v162, v239, v162
	v_exp_f32_e32 v172, v172
	v_add_f32_e32 v162, v240, v162
	v_exp_f32_e32 v173, v173
	v_add_f32_e32 v162, v241, v162
	v_exp_f32_e32 v174, v174
	s_waitcnt lgkmcnt(3)
	v_mfma_f32_32x32x16_bf16 v[80:95], v[138:141], v[118:121], v[80:95]
	v_add_f32_e32 v162, v242, v162
	v_exp_f32_e32 v175, v175
	v_add_f32_e32 v162, v243, v162
	v_exp_f32_e32 v176, v176
	v_add_f32_e32 v162, v244, v162
	v_exp_f32_e32 v177, v177
	s_waitcnt lgkmcnt(2)
	v_mfma_f32_32x32x16_bf16 v[64:79], v[142:145], v[118:121], v[64:79]
	v_add_u32_e32 v145, s14, v215
	ds_read_b128 v[138:141], v145 offset:49152
	ds_read_b128 v[142:145], v145 offset:57344
	v_add_f32_e32 v162, v245, v162
	v_exp_f32_e32 v230, v230
	v_add_f32_e32 v162, v246, v162
	v_exp_f32_e32 v188, v231
	v_add_f32_e32 v162, v247, v162
	v_exp_f32_e32 v186, v232
	s_waitcnt lgkmcnt(3)
	v_mfma_f32_32x32x16_bf16 v[80:95], v[130:133], v[114:117], v[80:95]
	v_add_f32_e32 v162, v248, v162
	v_exp_f32_e32 v233, v233
	v_add_f32_e32 v162, v249, v162
	v_exp_f32_e32 v234, v234
	v_add_f32_e32 v162, v250, v162
	v_exp_f32_e32 v235, v235
	s_waitcnt lgkmcnt(2)
	v_mfma_f32_32x32x16_bf16 v[64:79], v[134:137], v[114:117], v[64:79]
	v_add_u32_e32 v137, s14, v213
	ds_read_b128 v[130:133], v137 offset:49152
	ds_read_b128 v[134:137], v137 offset:57344
	v_add_f32_e32 v162, v251, v162
	v_exp_f32_e32 v236, v236
	v_add_f32_e32 v162, v252, v162
	v_exp_f32_e32 v237, v237
	v_add_f32_e32 v162, v253, v162
	v_exp_f32_e32 v194, v170
	s_waitcnt lgkmcnt(3)
	v_mfma_f32_32x32x16_bf16 v[80:95], v[138:141], v[110:113], v[80:95]
	v_add_f32_e32 v162, v171, v162
	v_add_f32_e32 v162, v172, v162
	v_add_f32_e32 v162, v173, v162
	v_add_f32_e32 v162, v174, v162
	v_add_f32_e32 v162, v175, v162
	v_add_f32_e32 v162, v176, v162
	s_waitcnt lgkmcnt(2)
	v_mfma_f32_32x32x16_bf16 v[64:79], v[142:145], v[110:113], v[64:79]
	v_add_u32_e32 v145, s14, v223
	ds_read_b128 v[138:141], v145 offset:49152
	ds_read_b128 v[142:145], v145 offset:57344
	v_add_f32_e32 v162, v177, v162
	v_add_f32_e32 v162, v230, v162
	v_add_f32_e32 v162, v188, v162
	v_add_f32_e32 v162, v186, v162
	v_add_f32_e32 v162, v233, v162
	v_add_f32_e32 v162, v234, v162
	s_waitcnt lgkmcnt(3)
	v_mfma_f32_32x32x16_bf16 v[80:95], v[130:133], v[106:109], v[80:95]
	v_add_f32_e32 v162, v235, v162
	v_add_f32_e32 v162, v236, v162
	v_add_f32_e32 v162, v237, v162
	v_add_f32_e32 v231, v194, v162
	v_mov_b32_e32 v232, v231
	v_cvt_pk_bf16_f32 v162, v238, v239
	s_waitcnt lgkmcnt(2)
	v_mfma_f32_32x32x16_bf16 v[64:79], v[134:137], v[106:109], v[64:79]
	v_add_u32_e32 v137, s14, v224
	ds_read_b128 v[130:133], v137 offset:49152
	ds_read_b128 v[134:137], v137 offset:57344
	v_cvt_pk_bf16_f32 v163, v240, v241
	v_cvt_pk_bf16_f32 v164, v242, v243
	v_cvt_pk_bf16_f32 v165, v244, v245
	v_cvt_pk_bf16_f32 v166, v246, v247
	v_cvt_pk_bf16_f32 v167, v248, v249
	s_waitcnt lgkmcnt(3)
	v_mfma_f32_32x32x16_bf16 v[80:95], v[138:141], v[102:105], v[80:95]
	v_cvt_pk_bf16_f32 v168, v250, v251
	v_cvt_pk_bf16_f32 v169, v252, v253
	v_cvt_pk_bf16_f32 v170, v171, v172
	v_cvt_pk_bf16_f32 v171, v173, v174
	v_cvt_pk_bf16_f32 v172, v175, v176
	s_waitcnt lgkmcnt(2)
	v_mfma_f32_32x32x16_bf16 v[64:79], v[142:145], v[102:105], v[64:79]
	v_cvt_pk_bf16_f32 v173, v177, v230
	v_cvt_pk_bf16_f32 v174, v188, v186
	v_cvt_pk_bf16_f32 v175, v233, v234
	v_cvt_pk_bf16_f32 v176, v235, v236
	v_cvt_pk_bf16_f32 v177, v237, v194
	s_waitcnt lgkmcnt(1)
	v_mfma_f32_32x32x16_bf16 v[80:95], v[130:133], v[98:101], v[80:95]
	s_nop 1
	v_permlane32_swap_b32_e32 v231, v232
	v_permlane32_swap_b32_e32 v162, v164
	v_permlane32_swap_b32_e32 v163, v165
	v_permlane32_swap_b32_e32 v166, v168
	s_waitcnt lgkmcnt(0)
	v_mfma_f32_32x32x16_bf16 v[64:79], v[134:137], v[98:101], v[64:79]
	v_permlane32_swap_b32_e32 v167, v169
	v_permlane32_swap_b32_e32 v170, v172
	v_permlane32_swap_b32_e32 v171, v173
	v_permlane32_swap_b32_e32 v174, v176
	v_permlane32_swap_b32_e32 v175, v177
	s_add_i32 s38, s38, 2
	s_cmp_ge_u32 s38, s36
	s_cselect_b64 s[10:11], -1, 0
	s_and_b64 vcc, exec, s[10:11]
	s_cbranch_vccnz .LBB0_275
	v_add_co_u32_e32 v130, vcc, 0xfffe8000, v180
	s_nop 1
	v_addc_co_u32_e32 v131, vcc, -1, v181, vcc
	global_load_dwordx4 v[134:137], v[130:131], off
	global_load_dwordx4 v[138:141], v[130:131], off offset:-512
	global_load_dwordx4 v[142:145], v[180:181], off
	s_nop 0
	global_load_dwordx4 v[130:133], v[180:181], off offset:-512
.LBB0_275:
	v_add_u32_e32 v186, s37, v212
	ds_read_b64_tr_b16 v[234:235], v186 offset:0x0
	ds_read_b64_tr_b16 v[236:237], v186 offset:0x800
	ds_read_b64_tr_b16 v[238:239], v186 offset:0x1000
	ds_read_b64_tr_b16 v[240:241], v186 offset:0x1800
	ds_read_b64_tr_b16 v[242:243], v186 offset:0x2000
	ds_read_b64_tr_b16 v[244:245], v186 offset:0x2800
	ds_read_b64_tr_b16 v[246:247], v186 offset:0x3000
	ds_read_b64_tr_b16 v[248:249], v186 offset:0x3800
	s_waitcnt lgkmcnt(0)
	s_nop 0
	v_mfma_f32_32x32x16_bf16 v[0:15], v[162:165], v[234:237], v[0:15]
	ds_read_b64_tr_b16 v[234:235], v186 offset:0x200
	ds_read_b64_tr_b16 v[236:237], v186 offset:0xa00
	s_add_i32 s16, s13, 0
	s_and_b64 vcc, exec, s[10:11]
	s_cbranch_vccnz .Lmy_sw_full
	s_waitcnt vmcnt(4)
	s_branch .Lmy_sw_join

; #define SWRITE(off, i) do { *(bf16x8*)((char*)V_lds + (off) + vst0) = sv0[i];          \
;     *(bf16x8*)((char*)V_lds + (off) + vst1) = sv1[i]; int kc = sc * 2;               \
;     *(bf16x8*)((char*)K_lds + (off) + KSWZ(sr, kc)) = sk0[i];                       \
;     *(bf16x8*)((char*)K_lds + (off) + KSWZ(32 + sr, kc)) = sk1[i]; } while (0)
; #define SWAIT() asm volatile("s_waitcnt vmcnt(4)" ::: "memory")
; #define RESC(a) do { if (__any((a) < 1.f)) { if (hi == 0) al_l[r32] = (a); asm volatile("s_waitcnt lgkmcnt(0)" ::: "memory"); \
;     _Pragma("unroll") for (int d = 0; d < 4; ++d) _Pragma("unroll") for (int r = 0; r < 16; ++r) o[d][r] *= al_l[crow(r, hi)]; } } while (0)
; __device__ __forceinline__ void partialSM(f32x16& p0, f32x16& p1, float& m_reg, float& mn, float& alpha) {
;     constexpr float C = SCALE * 1.4426950408889634f;
;     float pmax = p0[0];
; #pragma unroll
;     for (int r = 1; r < 16; ++r) pmax = fmaxf(pmax, p0[r]);
; #pragma unroll
;     for (int r = 0; r < 16; ++r) pmax = fmaxf(pmax, p1[r]);
;     { auto rr = __builtin_amdgcn_permlane32_swap(__float_as_uint(pmax), __float_as_uint(pmax), false, false);
;       pmax = fmaxf(__uint_as_float(rr[0]), __uint_as_float(rr[1])); }
;     if (__builtin_expect(__all(pmax - m_reg <= THR / SCALE), 1)) { mn = m_reg; alpha = 1.f; }
;     else { mn = fmaxf(m_reg, pmax); alpha = __builtin_amdgcn_exp2f((m_reg - mn) * C); m_reg = mn; }
;     float mnC = -mn * C;
; #pragma unroll
;     for (int r = 0; r < 16; ++r) p0[r] = fmaf(p0[r], C, mnC);
; #pragma unroll
;     for (int r = 0; r < 16; ++r) p1[r] = fmaf(p1[r], C, mnC);
; __device__ __forceinline__ void attn_dense_body(const bf16_t* __restrict__ Qb, const bf16_t* __restrict__ Kh, const bf16_t* __restrict__ Vh,
;                                                 bf16_t* __restrict__ Ob, int seq, char* lds, int dry) {
;     ...
;         pv_d0(o, vb0 + ov, pa0, pa1, pa2, pa3); partialSM(pA0, pA1, m_reg, mnA, alA);
;         SWAIT(); SWRITE(ow, 1);
;         RESC(alA); __syncthreads();
.Lmy_sw_join:
	v_add_u32_e32 v250, s16, v216
	ds_write_b128 v250, v[146:149]
	v_mfma_f32_32x32x16_bf16 v[0:15], v[166:169], v[238:241], v[0:15]
	ds_read_b64_tr_b16 v[238:239], v186 offset:0x1200
	ds_read_b64_tr_b16 v[240:241], v186 offset:0x1a00
	v_add_u32_e32 v250, s16, v217
	ds_write_b128 v250, v[158:161]
	v_mfma_f32_32x32x16_bf16 v[0:15], v[170:173], v[242:245], v[0:15]
	ds_read_b64_tr_b16 v[242:243], v186 offset:0x2200
	ds_read_b64_tr_b16 v[244:245], v186 offset:0x2a00
	v_add_u32_e32 v250, s16, v214
	ds_write_b128 v250, v[150:153] offset:49152
	v_mfma_f32_32x32x16_bf16 v[0:15], v[174:177], v[246:249], v[0:15]
	ds_read_b64_tr_b16 v[246:247], v186 offset:0x3200
	ds_read_b64_tr_b16 v[248:249], v186 offset:0x3a00
	v_add_u32_e32 v250, s16, v219
	ds_write_b128 v250, v[154:157] offset:49152
	s_waitcnt lgkmcnt(0)
	v_mfma_f32_32x32x16_bf16 v[48:63], v[162:165], v[234:237], v[48:63]
	ds_read_b64_tr_b16 v[234:235], v186 offset:0x400
	ds_read_b64_tr_b16 v[236:237], v186 offset:0xc00
	v_max_f32_e32 v250, v81, v81
	v_max_f32_e32 v251, v80, v80
	v_max_f32_e32 v250, v251, v250
	v_max3_f32 v250, v250, v82, v83
	v_max3_f32 v250, v250, v84, v85
	v_mfma_f32_32x32x16_bf16 v[48:63], v[166:169], v[238:241], v[48:63]
	ds_read_b64_tr_b16 v[238:239], v186 offset:0x1400
	ds_read_b64_tr_b16 v[240:241], v186 offset:0x1c00
	v_max3_f32 v250, v250, v86, v87
	v_max3_f32 v250, v250, v88, v89
	v_max3_f32 v250, v250, v90, v91
	v_max3_f32 v250, v250, v92, v93
	v_max3_f32 v250, v250, v94, v95
	v_mfma_f32_32x32x16_bf16 v[48:63], v[170:173], v[242:245], v[48:63]
	ds_read_b64_tr_b16 v[242:243], v186 offset:0x2400
	ds_read_b64_tr_b16 v[244:245], v186 offset:0x2c00
	v_max3_f32 v250, v250, v64, v65
	v_max3_f32 v250, v250, v66, v67
	v_max3_f32 v250, v250, v68, v69
	v_max3_f32 v250, v250, v70, v71
	v_max3_f32 v250, v250, v72, v73
	v_mfma_f32_32x32x16_bf16 v[48:63], v[174:177], v[246:249], v[48:63]
	ds_read_b64_tr_b16 v[246:247], v186 offset:0x3400
	ds_read_b64_tr_b16 v[248:249], v186 offset:0x3c00
	v_max3_f32 v250, v250, v74, v75
	v_max3_f32 v250, v250, v76, v77
	v_max3_f32 v250, v250, v78, v79
	v_mov_b32_e32 v251, v250
	s_waitcnt lgkmcnt(0)
	v_mfma_f32_32x32x16_bf16 v[32:47], v[162:165], v[234:237], v[32:47]
	ds_read_b64_tr_b16 v[234:235], v186 offset:0x600
	ds_read_b64_tr_b16 v[236:237], v186 offset:0xe00
	v_permlane32_swap_b32_e32 v250, v251
	v_max_f32_e32 v251, v251, v251
	v_max_f32_e32 v250, v250, v250
	v_max_f32_e32 v250, v250, v251
	v_mfma_f32_32x32x16_bf16 v[32:47], v[166:169], v[238:241], v[32:47]
	ds_read_b64_tr_b16 v[238:239], v186 offset:0x1600
	ds_read_b64_tr_b16 v[240:241], v186 offset:0x1e00
	v_sub_f32_e32 v251, v250, v229
	v_cmp_ge_f32_e32 vcc, s72, v251
	v_max_f32_e32 v251, v229, v229
	v_max_f32_e32 v250, v251, v250
	v_sub_f32_e32 v251, v229, v250
	v_mfma_f32_32x32x16_bf16 v[32:47], v[170:173], v[242:245], v[32:47]
	ds_read_b64_tr_b16 v[242:243], v186 offset:0x2600
	ds_read_b64_tr_b16 v[244:245], v186 offset:0x2e00
	v_mul_f32_e32 v251, 0x3e0293ee, v251
	v_exp_f32_e32 v251, v251
	v_mfma_f32_32x32x16_bf16 v[32:47], v[174:177], v[246:249], v[32:47]
	ds_read_b64_tr_b16 v[246:247], v186 offset:0x3600
	ds_read_b64_tr_b16 v[248:249], v186 offset:0x3e00
	s_cmp_eq_u64 vcc, exec
	s_cselect_b64 s[8:9], -1, 0
	s_nop 0
	v_cndmask_b32_e64 v252, v251, 1.0, s[8:9]
	v_cndmask_b32_e64 v253, v250, v229, s[8:9]
	v_mul_f32_e32 v188, 0xbe0293ee, v253
	s_waitcnt lgkmcnt(0)
	v_mfma_f32_32x32x16_bf16 v[16:31], v[162:165], v[234:237], v[16:31]
	v_fmamk_f32 v230, v85, 0x3e0293ee, v188
	v_fmamk_f32 v229, v83, 0x3e0293ee, v188
	v_fmamk_f32 v163, v80, 0x3e0293ee, v188
	v_fmamk_f32 v164, v82, 0x3e0293ee, v188
	v_fmamk_f32 v165, v86, 0x3e0293ee, v188
	v_mfma_f32_32x32x16_bf16 v[16:31], v[166:169], v[238:241], v[16:31]
	v_fmamk_f32 v167, v92, 0x3e0293ee, v188
	v_fmamk_f32 v169, v93, 0x3e0293ee, v188
	v_fmamk_f32 v168, v94, 0x3e0293ee, v188
	v_mfma_f32_32x32x16_bf16 v[16:31], v[170:173], v[242:245], v[16:31]
	v_fmamk_f32 v171, v88, 0x3e0293ee, v188
	v_fmamk_f32 v173, v89, 0x3e0293ee, v188
	v_fmamk_f32 v172, v90, 0x3e0293ee, v188
	v_fmamk_f32 v170, v95, 0x3e0293ee, v188
	v_mfma_f32_32x32x16_bf16 v[16:31], v[174:177], v[246:249], v[16:31]
	v_fmamk_f32 v177, v81, 0x3e0293ee, v188
	v_fmamk_f32 v176, v84, 0x3e0293ee, v188
	v_fmamk_f32 v175, v87, 0x3e0293ee, v188
	v_fmamk_f32 v174, v91, 0x3e0293ee, v188
	v_mov_b32_e32 v162, v252
	s_nop 0
	v_cmp_gt_f32_e32 vcc, 1.0, v162
	s_cbranch_vccz .LBB0_279
	s_and_saveexec_b64 s[14:15], s[6:7]
	ds_write_b32 v209, v162 offset:128
	s_or_b64 exec, exec, s[14:15]
	s_waitcnt lgkmcnt(0)
	v_add_u32_e32 v158, v179, v96
	ds_read_b128 v[146:149], v158 offset:224
	ds_read_b128 v[150:153], v158 offset:192
	ds_read_b128 v[154:157], v158 offset:160
	ds_read_b128 v[158:161], v158 offset:128
	s_waitcnt lgkmcnt(3)
	v_pk_mul_f32 v[12:13], v[12:13], v[146:147]
	s_waitcnt lgkmcnt(2)
	v_pk_mul_f32 v[8:9], v[8:9], v[150:151]
	s_waitcnt lgkmcnt(1)
	v_pk_mul_f32 v[4:5], v[4:5], v[154:155]
	v_pk_mul_f32 v[14:15], v[14:15], v[148:149]
	v_pk_mul_f32 v[10:11], v[10:11], v[152:153]
	v_pk_mul_f32 v[6:7], v[6:7], v[156:157]
	s_waitcnt lgkmcnt(0)
	v_pk_mul_f32 v[2:3], v[2:3], v[160:161]
	v_pk_mul_f32 v[0:1], v[0:1], v[158:159]
	v_pk_mul_f32 v[60:61], v[60:61], v[146:147]
	v_pk_mul_f32 v[56:57], v[56:57], v[150:151]
	v_pk_mul_f32 v[52:53], v[52:53], v[154:155]
	v_pk_mul_f32 v[62:63], v[62:63], v[148:149]
	v_pk_mul_f32 v[58:59], v[58:59], v[152:153]
	v_pk_mul_f32 v[54:55], v[54:55], v[156:157]
	v_pk_mul_f32 v[50:51], v[50:51], v[160:161]
	v_pk_mul_f32 v[48:49], v[48:49], v[158:159]
	v_pk_mul_f32 v[44:45], v[44:45], v[146:147]
	v_pk_mul_f32 v[40:41], v[40:41], v[150:151]
	v_pk_mul_f32 v[36:37], v[36:37], v[154:155]
	v_pk_mul_f32 v[46:47], v[46:47], v[148:149]
	v_pk_mul_f32 v[42:43], v[42:43], v[152:153]
	v_pk_mul_f32 v[38:39], v[38:39], v[156:157]
	v_pk_mul_f32 v[34:35], v[34:35], v[160:161]
	v_pk_mul_f32 v[32:33], v[32:33], v[158:159]
	v_pk_mul_f32 v[28:29], v[28:29], v[146:147]
	v_pk_mul_f32 v[24:25], v[24:25], v[150:151]
	v_pk_mul_f32 v[20:21], v[20:21], v[154:155]
	v_pk_mul_f32 v[30:31], v[30:31], v[148:149]
	v_pk_mul_f32 v[26:27], v[26:27], v[152:153]
	v_pk_mul_f32 v[22:23], v[22:23], v[156:157]
	v_pk_mul_f32 v[18:19], v[18:19], v[160:161]
	v_pk_mul_f32 v[16:17], v[16:17], v[158:159]
; #define SBAR() __builtin_amdgcn_sched_barrier(0)
; #define SWRITE(off, i) do { *(bf16x8*)((char*)V_lds + (off) + vst0) = sv0[i];          \
;     *(bf16x8*)((char*)V_lds + (off) + vst1) = sv1[i]; int kc = sc * 2;               \
;     *(bf16x8*)((char*)K_lds + (off) + KSWZ(sr, kc)) = sk0[i];                       \
;     *(bf16x8*)((char*)K_lds + (off) + KSWZ(32 + sr, kc)) = sk1[i]; } while (0)
; #define SWAIT() asm volatile("s_waitcnt vmcnt(4)" ::: "memory")
; #define RESC(a) do { if (__any((a) < 1.f)) { if (hi == 0) al_l[r32] = (a); asm volatile("s_waitcnt lgkmcnt(0)" ::: "memory"); \
;     _Pragma("unroll") for (int d = 0; d < 4; ++d) _Pragma("unroll") for (int r = 0; r < 16; ++r) o[d][r] *= al_l[crow(r, hi)]; } } while (0)
; __device__ __forceinline__ void attn_dense_body(const bf16_t* __restrict__ Qb, const bf16_t* __restrict__ Kh, const bf16_t* __restrict__ Vh,
;                                                 bf16_t* __restrict__ Ob, int seq, char* lds, int dry) {
;     ...
;         pv_d0(o, vb0 + ov, pa0, pa1, pa2, pa3); partialSM(pA0, pA1, m_reg, mnA, alA);
;         SWAIT(); SWRITE(ow, 1);
;         RESC(alA); __syncthreads();
;         { const int t_ = ov; ov = oq; oq = ow; ow = t_; }
;     }
;     SBAR(); qkt(pB0, pB1, (bf16_t*)((char*)K_lds + oq), qr, r32, hi);
;     finishSM(pA0, pA1, alA, l_reg, pa0, pa1, pa2, pa3); SBAR();
;     pv_d0(o, vb0 + ov, pa0, pa1, pa2, pa3); partialSM(pB0, pB1, m_reg, mnB, alB);
.LBB0_279:
	v_mov_b32_e32 v166, v253
	v_mov_b32_e32 v146, v188
	v_pk_fma_f32 v[160:161], v[64:65], s[20:21], v[146:147] op_sel_hi:[1,0,0]
	v_add_f32_e32 v64, v226, v227
	v_fmac_f32_e32 v64, v225, v210
	v_add_f32_e32 v210, v231, v232
	s_mov_b64 s[8:9], 0x60000
	v_pk_fma_f32 v[158:159], v[66:67], s[20:21], v[146:147] op_sel_hi:[1,0,0]
	v_pk_fma_f32 v[156:157], v[68:69], s[20:21], v[146:147] op_sel_hi:[1,0,0]
	v_pk_fma_f32 v[154:155], v[70:71], s[20:21], v[146:147] op_sel_hi:[1,0,0]
	v_pk_fma_f32 v[152:153], v[72:73], s[20:21], v[146:147] op_sel_hi:[1,0,0]
	v_pk_fma_f32 v[150:151], v[74:75], s[20:21], v[146:147] op_sel_hi:[1,0,0]
	v_pk_fma_f32 v[148:149], v[76:77], s[20:21], v[146:147] op_sel_hi:[1,0,0]
	v_pk_fma_f32 v[146:147], v[78:79], s[20:21], v[146:147] op_sel_hi:[1,0,0]
	v_fmac_f32_e32 v210, v64, v228
	v_lshl_add_u64 v[180:181], v[180:181], 0, s[8:9]
	s_and_b64 vcc, exec, s[10:11]
	s_waitcnt lgkmcnt(0)
	s_barrier
	s_cbranch_vccnz .LBB0_281
	s_mov_b32 s8, s37
	s_mov_b32 s37, s13
	v_mov_b32_e32 v225, v162
	s_branch .LBB0_269
.LBB0_281:
	v_exp_f32_e32 v163, v163
	v_exp_f32_e32 v177, v177
	v_exp_f32_e32 v164, v164
	v_exp_f32_e32 v229, v229
	v_exp_f32_e32 v176, v176
	v_exp_f32_e32 v230, v230
	v_exp_f32_e32 v165, v165
	v_exp_f32_e32 v175, v175
	v_exp_f32_e32 v171, v171
	v_exp_f32_e32 v173, v173
	v_exp_f32_e32 v172, v172
	v_exp_f32_e32 v174, v174
	v_exp_f32_e32 v167, v167
	v_exp_f32_e32 v169, v169
	v_exp_f32_e32 v168, v168
	v_exp_f32_e32 v170, v170
	v_add_u32_e32 v68, s16, v220
	ds_read_b128 v[64:67], v68 offset:49152
	ds_read_b128 v[68:71], v68 offset:57344
	v_add_u32_e32 v130, s16, v222
	s_waitcnt lgkmcnt(1)
	v_mfma_f32_32x32x16_bf16 v[80:95], v[64:67], v[126:129], 0
	s_waitcnt lgkmcnt(0)
	v_mfma_f32_32x32x16_bf16 v[64:79], v[68:71], v[126:129], 0
	ds_read_b128 v[126:129], v130 offset:49152
	ds_read_b128 v[130:133], v130 offset:57344
	s_waitcnt lgkmcnt(1)
	v_mfma_f32_32x32x16_bf16 v[80:95], v[126:129], v[122:125], v[80:95]
	v_add_u32_e32 v126, s16, v221
	s_waitcnt lgkmcnt(0)
	v_mfma_f32_32x32x16_bf16 v[64:79], v[130:133], v[122:125], v[64:79]
	ds_read_b128 v[122:125], v126 offset:49152
	ds_read_b128 v[126:129], v126 offset:57344
	s_waitcnt lgkmcnt(1)
	v_mfma_f32_32x32x16_bf16 v[80:95], v[122:125], v[118:121], v[80:95]
	v_add_u32_e32 v122, s16, v218
	s_waitcnt lgkmcnt(0)
	v_mfma_f32_32x32x16_bf16 v[64:79], v[126:129], v[118:121], v[64:79]
	ds_read_b128 v[118:121], v122 offset:49152
	ds_read_b128 v[122:125], v122 offset:57344
	s_waitcnt lgkmcnt(1)
	v_mfma_f32_32x32x16_bf16 v[80:95], v[118:121], v[114:117], v[80:95]
	v_add_u32_e32 v118, s16, v215
	s_waitcnt lgkmcnt(0)
	v_mfma_f32_32x32x16_bf16 v[64:79], v[122:125], v[114:117], v[64:79]
	ds_read_b128 v[114:117], v118 offset:49152
	ds_read_b128 v[118:121], v118 offset:57344
	v_exp_f32_e32 v122, v146
	v_exp_f32_e32 v123, v147
	s_waitcnt lgkmcnt(1)
	v_mfma_f32_32x32x16_bf16 v[80:95], v[114:117], v[110:113], v[80:95]
	v_add_u32_e32 v114, s16, v213
	s_waitcnt lgkmcnt(0)
	v_mfma_f32_32x32x16_bf16 v[64:79], v[118:121], v[110:113], v[64:79]
	ds_read_b128 v[110:113], v114 offset:49152
	ds_read_b128 v[114:117], v114 offset:57344
	v_exp_f32_e32 v118, v150
	v_exp_f32_e32 v119, v151
	v_exp_f32_e32 v120, v148
	v_exp_f32_e32 v121, v149
	s_waitcnt lgkmcnt(1)
	v_mfma_f32_32x32x16_bf16 v[80:95], v[110:113], v[106:109], v[80:95]
	v_add_u32_e32 v110, s16, v223
	s_waitcnt lgkmcnt(0)
	v_mfma_f32_32x32x16_bf16 v[64:79], v[114:117], v[106:109], v[64:79]
	ds_read_b128 v[106:109], v110 offset:49152
	ds_read_b128 v[110:113], v110 offset:57344
	v_exp_f32_e32 v114, v154
	v_exp_f32_e32 v115, v155
	v_exp_f32_e32 v116, v152
	v_exp_f32_e32 v117, v153
	s_waitcnt lgkmcnt(1)
	v_mfma_f32_32x32x16_bf16 v[80:95], v[106:109], v[102:105], v[80:95]
	v_add_u32_e32 v106, s16, v224
	s_waitcnt lgkmcnt(0)
	v_mfma_f32_32x32x16_bf16 v[64:79], v[110:113], v[102:105], v[64:79]
	ds_read_b128 v[102:105], v106 offset:49152
	ds_read_b128 v[106:109], v106 offset:57344
	v_exp_f32_e32 v110, v158
	v_exp_f32_e32 v111, v159
	v_exp_f32_e32 v112, v156
	v_exp_f32_e32 v113, v157
	s_waitcnt lgkmcnt(1)
	v_mfma_f32_32x32x16_bf16 v[80:95], v[102:105], v[98:101], v[80:95]
	s_waitcnt lgkmcnt(0)
	v_mfma_f32_32x32x16_bf16 v[64:79], v[106:109], v[98:101], v[64:79]
	v_add_f32_e32 v98, 0, v163
	v_add_f32_e32 v98, v177, v98
	v_add_f32_e32 v98, v164, v98
	v_add_f32_e32 v98, v229, v98
	v_add_f32_e32 v98, v176, v98
	v_add_f32_e32 v98, v230, v98
	v_add_f32_e32 v98, v165, v98
	v_add_f32_e32 v98, v175, v98
	v_add_f32_e32 v98, v171, v98
	v_add_f32_e32 v98, v173, v98
	v_add_f32_e32 v98, v172, v98
	v_add_f32_e32 v98, v174, v98
	v_exp_f32_e32 v108, v160
	v_add_f32_e32 v98, v167, v98
	v_exp_f32_e32 v109, v161
	v_add_f32_e32 v98, v169, v98
	v_add_f32_e32 v98, v168, v98
	v_add_f32_e32 v98, v170, v98
	v_add_f32_e32 v98, v108, v98
	v_add_f32_e32 v98, v109, v98
	v_add_f32_e32 v98, v110, v98
	v_add_f32_e32 v98, v111, v98
	v_add_f32_e32 v98, v112, v98
	v_add_f32_e32 v98, v113, v98
	v_add_f32_e32 v98, v114, v98
	v_add_f32_e32 v98, v115, v98
	v_add_f32_e32 v98, v116, v98
	v_add_f32_e32 v98, v117, v98
	v_add_f32_e32 v98, v118, v98
	v_add_f32_e32 v98, v119, v98
	v_add_f32_e32 v98, v120, v98
	v_add_f32_e32 v98, v121, v98
	v_add_f32_e32 v98, v122, v98
	v_add_f32_e32 v102, v123, v98
	v_mov_b32_e32 v103, v102
	v_cvt_pk_bf16_f32 v98, v163, v177
	v_cvt_pk_bf16_f32 v99, v164, v229
	v_cvt_pk_bf16_f32 v100, v176, v230
	v_cvt_pk_bf16_f32 v101, v165, v175
	s_nop 1
	v_permlane32_swap_b32_e32 v102, v103
	v_permlane32_swap_b32_e32 v98, v100
	v_permlane32_swap_b32_e32 v99, v101
	v_cvt_pk_bf16_f32 v104, v171, v173
	v_cvt_pk_bf16_f32 v105, v172, v174
	v_cvt_pk_bf16_f32 v106, v167, v169
	v_cvt_pk_bf16_f32 v107, v168, v170
	v_cvt_pk_bf16_f32 v108, v108, v109
	v_cvt_pk_bf16_f32 v109, v110, v111
	v_cvt_pk_bf16_f32 v110, v112, v113
	v_cvt_pk_bf16_f32 v111, v114, v115
	v_cvt_pk_bf16_f32 v112, v116, v117
	v_cvt_pk_bf16_f32 v113, v118, v119
	v_cvt_pk_bf16_f32 v114, v120, v121
	v_cvt_pk_bf16_f32 v115, v122, v123
	s_nop 0
	v_permlane32_swap_b32_e32 v104, v106
	v_permlane32_swap_b32_e32 v105, v107
	v_permlane32_swap_b32_e32 v108, v110
	v_permlane32_swap_b32_e32 v109, v111
	v_permlane32_swap_b32_e32 v112, v114
	v_permlane32_swap_b32_e32 v113, v115
	v_add_u32_e32 v132, s12, v212
	ds_read_b64_tr_b16 v[116:117], v132 offset:0
	ds_read_b64_tr_b16 v[118:119], v132 offset:0x800
	ds_read_b64_tr_b16 v[120:121], v132 offset:0x1000
	ds_read_b64_tr_b16 v[122:123], v132 offset:0x1800
	ds_read_b64_tr_b16 v[124:125], v132 offset:0x2000
	ds_read_b64_tr_b16 v[126:127], v132 offset:0x2800
	ds_read_b64_tr_b16 v[128:129], v132 offset:0x3000
	ds_read_b64_tr_b16 v[130:131], v132 offset:0x3800
	s_waitcnt lgkmcnt(0)
; #define RESC(a) do { if (__any((a) < 1.f)) { if (hi == 0) al_l[r32] = (a); asm volatile("s_waitcnt lgkmcnt(0)" ::: "memory"); \
;     _Pragma("unroll") for (int d = 0; d < 4; ++d) _Pragma("unroll") for (int r = 0; r < 16; ++r) o[d][r] *= al_l[crow(r, hi)]; } } while (0)
; __device__ __forceinline__ void partialSM(f32x16& p0, f32x16& p1, float& m_reg, float& mn, float& alpha) {
;     constexpr float C = SCALE * 1.4426950408889634f;
;     float pmax = p0[0];
; #pragma unroll
;     for (int r = 1; r < 16; ++r) pmax = fmaxf(pmax, p0[r]);
; #pragma unroll
;     for (int r = 0; r < 16; ++r) pmax = fmaxf(pmax, p1[r]);
;     { auto rr = __builtin_amdgcn_permlane32_swap(__float_as_uint(pmax), __float_as_uint(pmax), false, false);
;       pmax = fmaxf(__uint_as_float(rr[0]), __uint_as_float(rr[1])); }
;     if (__builtin_expect(__all(pmax - m_reg <= THR / SCALE), 1)) { mn = m_reg; alpha = 1.f; }
;     else { mn = fmaxf(m_reg, pmax); alpha = __builtin_amdgcn_exp2f((m_reg - mn) * C); m_reg = mn; }
; __device__ __forceinline__ void attn_dense_body(const bf16_t* __restrict__ Qb, const bf16_t* __restrict__ Kh, const bf16_t* __restrict__ Vh,
;                                                 bf16_t* __restrict__ Ob, int seq, char* lds, int dry) {
;     ...
;     pv_d0(o, vb0 + ov, pa0, pa1, pa2, pa3); partialSM(pB0, pB1, m_reg, mnB, alB);
;     RESC(alB);
	s_nop 0
	v_mfma_f32_32x32x16_bf16 v[0:15], v[98:101], v[116:119], v[0:15]
	ds_read_b64_tr_b16 v[116:117], v132 offset:0x200
	ds_read_b64_tr_b16 v[118:119], v132 offset:0xa00
	v_mfma_f32_32x32x16_bf16 v[0:15], v[104:107], v[120:123], v[0:15]
	ds_read_b64_tr_b16 v[120:121], v132 offset:0x1200
	ds_read_b64_tr_b16 v[122:123], v132 offset:0x1a00
	v_mfma_f32_32x32x16_bf16 v[0:15], v[108:111], v[124:127], v[0:15]
	ds_read_b64_tr_b16 v[124:125], v132 offset:0x2200
	ds_read_b64_tr_b16 v[126:127], v132 offset:0x2a00
	v_mfma_f32_32x32x16_bf16 v[0:15], v[112:115], v[128:131], v[0:15]
	ds_read_b64_tr_b16 v[128:129], v132 offset:0x3200
	ds_read_b64_tr_b16 v[130:131], v132 offset:0x3a00
	s_waitcnt lgkmcnt(0)
	v_mfma_f32_32x32x16_bf16 v[48:63], v[98:101], v[116:119], v[48:63]
	ds_read_b64_tr_b16 v[116:117], v132 offset:0x400
	ds_read_b64_tr_b16 v[118:119], v132 offset:0xc00
	v_mfma_f32_32x32x16_bf16 v[48:63], v[104:107], v[120:123], v[48:63]
	ds_read_b64_tr_b16 v[120:121], v132 offset:0x1400
	ds_read_b64_tr_b16 v[122:123], v132 offset:0x1c00
	v_mfma_f32_32x32x16_bf16 v[48:63], v[108:111], v[124:127], v[48:63]
	ds_read_b64_tr_b16 v[124:125], v132 offset:0x2400
	ds_read_b64_tr_b16 v[126:127], v132 offset:0x2c00
	v_mfma_f32_32x32x16_bf16 v[48:63], v[112:115], v[128:131], v[48:63]
	ds_read_b64_tr_b16 v[128:129], v132 offset:0x3400
	ds_read_b64_tr_b16 v[130:131], v132 offset:0x3c00
	s_waitcnt lgkmcnt(0)
	v_mfma_f32_32x32x16_bf16 v[32:47], v[98:101], v[116:119], v[32:47]
	ds_read_b64_tr_b16 v[116:117], v132 offset:0x600
	ds_read_b64_tr_b16 v[118:119], v132 offset:0xe00
	v_mfma_f32_32x32x16_bf16 v[32:47], v[104:107], v[120:123], v[32:47]
	ds_read_b64_tr_b16 v[120:121], v132 offset:0x1600
	ds_read_b64_tr_b16 v[122:123], v132 offset:0x1e00
	v_mfma_f32_32x32x16_bf16 v[32:47], v[108:111], v[124:127], v[32:47]
	ds_read_b64_tr_b16 v[124:125], v132 offset:0x2600
	ds_read_b64_tr_b16 v[126:127], v132 offset:0x2e00
	v_mfma_f32_32x32x16_bf16 v[32:47], v[112:115], v[128:131], v[32:47]
	ds_read_b64_tr_b16 v[128:129], v132 offset:0x3600
	ds_read_b64_tr_b16 v[130:131], v132 offset:0x3e00
	s_waitcnt lgkmcnt(0)
	v_mfma_f32_32x32x16_bf16 v[16:31], v[98:101], v[116:119], v[16:31]
	v_max_f32_e32 v98, v81, v81
	v_max_f32_e32 v99, v80, v80
	v_max_f32_e32 v98, v99, v98
	v_max3_f32 v98, v98, v82, v83
	v_max3_f32 v98, v98, v84, v85
	v_max3_f32 v98, v98, v86, v87
	v_max3_f32 v98, v98, v88, v89
	v_max3_f32 v98, v98, v90, v91
	v_max3_f32 v98, v98, v92, v93
	v_mfma_f32_32x32x16_bf16 v[16:31], v[104:107], v[120:123], v[16:31]
	v_max3_f32 v98, v98, v94, v95
	v_max3_f32 v98, v98, v64, v65
	v_max3_f32 v98, v98, v66, v67
	v_max3_f32 v98, v98, v68, v69
	v_max3_f32 v98, v98, v70, v71
	v_max3_f32 v98, v98, v72, v73
	v_max3_f32 v98, v98, v74, v75
	v_max3_f32 v98, v98, v76, v77
	v_mfma_f32_32x32x16_bf16 v[16:31], v[108:111], v[124:127], v[16:31]
	v_max3_f32 v98, v98, v78, v79
	v_mov_b32_e32 v99, v98
	s_nop 1
	v_permlane32_swap_b32_e32 v98, v99
	v_max_f32_e32 v99, v99, v99
	v_max_f32_e32 v98, v98, v98
	v_max_f32_e32 v98, v98, v99
	v_sub_f32_e32 v99, v98, v166
	v_cmp_ge_f32_e32 vcc, s72, v99
	v_max_f32_e32 v99, v166, v166
	v_max_f32_e32 v99, v99, v98
	v_mfma_f32_32x32x16_bf16 v[16:31], v[112:115], v[128:131], v[16:31]
	v_sub_f32_e32 v98, v166, v99
	v_mul_f32_e32 v98, 0x3e0293ee, v98
	v_exp_f32_e32 v98, v98
	s_cmp_eq_u64 vcc, exec
	s_cselect_b64 s[8:9], -1, 0
	v_cndmask_b32_e64 v98, v98, 1.0, s[8:9]
	v_cmp_gt_f32_e32 vcc, 1.0, v98
	s_cbranch_vccz .LBB0_285
	s_and_saveexec_b64 s[10:11], s[6:7]
	ds_write_b32 v209, v98 offset:128
	s_or_b64 exec, exec, s[10:11]
	s_waitcnt lgkmcnt(0)
	v_add_u32_e32 v100, v179, v96
	ds_read_b128 v[104:107], v100 offset:224
	ds_read_b128 v[108:111], v100 offset:192
	ds_read_b128 v[112:115], v100 offset:160
	ds_read_b128 v[116:119], v100 offset:128
	s_waitcnt lgkmcnt(3)
	v_pk_mul_f32 v[12:13], v[12:13], v[104:105]
	s_waitcnt lgkmcnt(2)
	v_pk_mul_f32 v[8:9], v[8:9], v[108:109]
	s_waitcnt lgkmcnt(1)
	v_pk_mul_f32 v[4:5], v[4:5], v[112:113]
	v_pk_mul_f32 v[14:15], v[14:15], v[106:107]
	v_pk_mul_f32 v[10:11], v[10:11], v[110:111]
	v_pk_mul_f32 v[6:7], v[6:7], v[114:115]
	s_waitcnt lgkmcnt(0)
	v_pk_mul_f32 v[2:3], v[2:3], v[118:119]
	v_pk_mul_f32 v[0:1], v[0:1], v[116:117]
	v_pk_mul_f32 v[60:61], v[60:61], v[104:105]
	v_pk_mul_f32 v[56:57], v[56:57], v[108:109]
	v_pk_mul_f32 v[52:53], v[52:53], v[112:113]
	v_pk_mul_f32 v[62:63], v[62:63], v[106:107]
	v_pk_mul_f32 v[58:59], v[58:59], v[110:111]
	v_pk_mul_f32 v[54:55], v[54:55], v[114:115]
	v_pk_mul_f32 v[50:51], v[50:51], v[118:119]
	v_pk_mul_f32 v[48:49], v[48:49], v[116:117]
	v_pk_mul_f32 v[44:45], v[44:45], v[104:105]
	v_pk_mul_f32 v[40:41], v[40:41], v[108:109]
	v_pk_mul_f32 v[36:37], v[36:37], v[112:113]
	v_pk_mul_f32 v[46:47], v[46:47], v[106:107]
	v_pk_mul_f32 v[42:43], v[42:43], v[110:111]
	v_pk_mul_f32 v[38:39], v[38:39], v[114:115]
	v_pk_mul_f32 v[34:35], v[34:35], v[118:119]
	v_pk_mul_f32 v[32:33], v[32:33], v[116:117]
	v_pk_mul_f32 v[28:29], v[28:29], v[104:105]
	v_pk_mul_f32 v[24:25], v[24:25], v[108:109]
	v_pk_mul_f32 v[20:21], v[20:21], v[112:113]
	v_pk_mul_f32 v[30:31], v[30:31], v[106:107]
	v_pk_mul_f32 v[26:27], v[26:27], v[110:111]
	v_pk_mul_f32 v[22:23], v[22:23], v[114:115]
	v_pk_mul_f32 v[18:19], v[18:19], v[118:119]
	v_pk_mul_f32 v[16:17], v[16:17], v[116:117]
